# P5 per-head query epilogue: norm partials and rope frequencies loaded once up front, no per-row-group waits behind stores
# baseline (speedup 1.0000x reference)
.LBB0_620:
	v_lshl_add_u32 v146, s6, 8, v1
	v_ashrrev_i32_e32 v147, 31, v146
	v_lshlrev_b64 v[142:143], 5, v[146:147]
	v_lshl_add_u64 v[142:143], s[10:11], 0, v[142:143]
	global_load_dwordx4 v[162:165], v[142:143], off
	global_load_dwordx4 v[182:185], v[142:143], off offset:512
	global_load_dwordx4 v[186:189], v[142:143], off offset:1024
	global_load_dwordx4 v[190:193], v[142:143], off offset:1536
	v_add_co_u32_e32 v218, vcc, 0x1000, v142
	s_nop 1
	v_addc_co_u32_e32 v219, vcc, 0, v143, vcc
	global_load_dwordx4 v[194:197], v[218:219], off
	global_load_dwordx4 v[198:201], v[218:219], off offset:512
	global_load_dwordx4 v[202:205], v[218:219], off offset:1024
	global_load_dwordx4 v[206:209], v[218:219], off offset:1536
	global_load_dwordx4 v[210:213], v[138:139], off
	s_cmp_gt_i32 s8, 1
	s_cselect_b64 s[38:39], -1, 0
	s_mov_b64 s[6:7], -1
	v_lshlrev_b32_e32 v134, 1, v136
	v_lshlrev_b64 v[150:151], 3, v[146:147]
	s_and_b64 vcc, exec, s[38:39]
	s_waitcnt vmcnt(0)
	v_add_f32_e32 v142, v162, v163
	v_add_f32_e32 v143, v164, v165
	v_add_f32_e32 v142, v142, v143
	v_fmamk_f32 v142, v142, 0x3b800000, v158
	v_rsq_f32_e32 v142, v142
	s_nop 0
	v_mul_f32_e32 v148, 0x3e16c740, v142
	s_cbranch_vccz .LBB0_622
	v_mov_b32_e32 v152, v210
	v_mov_b32_e32 v153, v211
	v_mov_b32_e32 v154, v212
	v_mov_b32_e32 v155, v213
	v_and_b32_e32 v142, 0x1fcf, v146
	v_cvt_f32_u32_e32 v142, v142
	v_mul_f32_e32 v143, v152, v142
	v_mul_f32_e32 v144, v153, v142
	v_mul_f32_e32 v147, v154, v142
	v_mul_f32_e32 v154, v155, v142
	v_cvt_f64_f32_e32 v[142:143], v143
	v_cvt_f64_f32_e32 v[144:145], v144
	v_mul_f64 v[162:163], v[142:143], s[42:43]
	v_cvt_f64_f32_e32 v[152:153], v147
	v_mul_f64 v[164:165], v[144:145], s[42:43]
	v_rndne_f64_e32 v[162:163], v[162:163]
	v_mul_f64 v[166:167], v[152:153], s[42:43]
	v_rndne_f64_e32 v[164:165], v[164:165]
	v_fma_f64 v[142:143], v[142:143], s[42:43], -v[162:163]
	v_rndne_f64_e32 v[166:167], v[166:167]
	v_fma_f64 v[144:145], v[144:145], s[42:43], -v[164:165]
	v_mul_f64 v[142:143], v[142:143], s[44:45]
	v_fma_f64 v[152:153], v[152:153], s[42:43], -v[166:167]
	v_mul_f64 v[144:145], v[144:145], s[44:45]
	v_cvt_f32_f64_e32 v142, v[142:143]
	v_mul_f64 v[152:153], v[152:153], s[44:45]
	v_cvt_f32_f64_e32 v143, v[144:145]
	v_mul_f32_e32 v145, v142, v142
	v_cvt_i32_f64_e32 v147, v[162:163]
	v_cvt_i32_f64_e32 v161, v[164:165]
	v_cvt_f32_f64_e32 v144, v[152:153]
	v_mul_f32_e32 v152, v143, v143
	v_fmamk_f32 v163, v145, 0x3638ef1d, v159
	v_fmamk_f32 v164, v145, 0xb493f27e, v160
	v_cvt_i32_f64_e32 v162, v[166:167]
	v_mul_f32_e32 v153, v144, v144
	v_fmamk_f32 v165, v152, 0x3638ef1d, v159
	v_fmamk_f32 v166, v152, 0xb493f27e, v160
	v_fmaak_f32 v163, v145, v163, 0x3c088888
	v_fmaak_f32 v164, v145, v164, 0xbab60b61
	v_fmamk_f32 v167, v153, 0x3638ef1d, v159
	v_fmamk_f32 v170, v153, 0xb493f27e, v160
	v_fmaak_f32 v165, v152, v165, 0x3c088888
	v_fmaak_f32 v166, v152, v166, 0xbab60b61
	v_fmaak_f32 v163, v145, v163, 0xbe2aaaab
	v_fmaak_f32 v164, v145, v164, 0x3d2aaaab
	v_and_b32_e32 v147, 3, v147
	v_fmaak_f32 v167, v153, v167, 0x3c088888
	v_fmaak_f32 v170, v153, v170, 0xbab60b61
	v_fmaak_f32 v165, v152, v165, 0xbe2aaaab
	v_fmaak_f32 v166, v152, v166, 0x3d2aaaab
	v_fma_f32 v163, v145, v163, 1.0
	v_fma_f32 v164, v145, v164, -0.5
	v_and_b32_e32 v161, 3, v161
	v_fmaak_f32 v167, v153, v167, 0xbe2aaaab
	v_fmaak_f32 v170, v153, v170, 0x3d2aaaab
	v_fma_f32 v165, v152, v165, 1.0
	v_fma_f32 v166, v152, v166, -0.5
	v_mul_f32_e32 v142, v163, v142
	v_fma_f32 v145, v145, v164, 1.0
	v_cmp_eq_u32_e32 vcc, 2, v147
	v_and_b32_e32 v162, 3, v162
	v_fma_f32 v167, v153, v167, 1.0
	v_fma_f32 v170, v153, v170, -0.5
	v_mul_f32_e32 v143, v165, v143
	v_fma_f32 v152, v152, v166, 1.0
	v_cndmask_b32_e64 v163, v142, -v145, vcc
	v_cndmask_b32_e32 v164, v145, v142, vcc
	v_cmp_eq_u32_e32 vcc, 2, v161
	v_mul_f32_e32 v144, v167, v144
	v_fma_f32 v153, v153, v170, 1.0
	v_cndmask_b32_e64 v165, v143, -v152, vcc
	v_cndmask_b32_e32 v166, v152, v143, vcc
	v_cmp_eq_u32_e32 vcc, 2, v162
	v_cvt_f64_f32_e32 v[154:155], v154
	v_mul_f64 v[168:169], v[154:155], s[42:43]
	v_cndmask_b32_e64 v167, v144, -v153, vcc
	v_cndmask_b32_e32 v170, v153, v144, vcc
	v_cmp_eq_u32_e32 vcc, 1, v147
	v_rndne_f64_e32 v[168:169], v[168:169]
	v_fma_f64 v[154:155], v[154:155], s[42:43], -v[168:169]
	v_cndmask_b32_e64 v163, v163, -v142, vcc
	v_cndmask_b32_e64 v164, -v164, v145, vcc
	v_cmp_eq_u32_e32 vcc, 1, v161
	v_mul_f64 v[154:155], v[154:155], s[44:45]
	s_nop 0
	v_cndmask_b32_e64 v165, v165, -v143, vcc
	v_cndmask_b32_e64 v166, -v166, v152, vcc
	v_cmp_eq_u32_e32 vcc, 1, v162
	s_nop 1
	v_cndmask_b32_e64 v167, v167, -v144, vcc
	v_cndmask_b32_e64 v170, -v170, v153, vcc
	v_cmp_eq_u32_e32 vcc, 0, v147
	s_nop 1
	v_cndmask_b32_e32 v147, v163, v145, vcc
	v_cndmask_b32_e32 v163, v164, v142, vcc
	v_cmp_eq_u32_e32 vcc, 0, v161
	v_cvt_f32_f64_e32 v142, v[154:155]
	s_nop 0
	v_cndmask_b32_e32 v161, v165, v152, vcc
	v_cndmask_b32_e32 v164, v166, v143, vcc
	v_cmp_eq_u32_e32 vcc, 0, v162
	v_cvt_i32_f64_e32 v143, v[168:169]
	v_and_b32_e32 v143, 3, v143
	v_cndmask_b32_e32 v165, v170, v144, vcc
	v_mul_f32_e32 v144, v142, v142
	v_fmamk_f32 v145, v144, 0x3638ef1d, v159
	v_fmaak_f32 v145, v144, v145, 0x3c088888
	v_fmaak_f32 v145, v144, v145, 0xbe2aaaab
	v_fma_f32 v145, v144, v145, 1.0
	v_mul_f32_e32 v142, v145, v142
	v_fmamk_f32 v145, v144, 0xb493f27e, v160
	v_fmaak_f32 v145, v144, v145, 0xbab60b61
	v_fmaak_f32 v145, v144, v145, 0x3d2aaaab
	v_fma_f32 v145, v144, v145, -0.5
	v_cndmask_b32_e32 v162, v167, v153, vcc
	v_fma_f32 v144, v144, v145, 1.0
	v_cmp_eq_u32_e32 vcc, 2, v143
	v_cmp_eq_u32_e64 s[6:7], 1, v143
	s_nop 0
	v_cndmask_b32_e64 v145, v142, -v144, vcc
	v_cndmask_b32_e32 v152, v144, v142, vcc
	v_cndmask_b32_e64 v145, v145, -v142, s[6:7]
	v_cndmask_b32_e64 v152, -v152, v144, s[6:7]
	v_cmp_eq_u32_e32 vcc, 0, v143
	v_mul_f32_e32 v143, v126, v148
	s_mov_b64 s[6:7], 0
	v_cndmask_b32_e32 v154, v145, v144, vcc
	v_cndmask_b32_e32 v155, v152, v142, vcc
	v_mul_f32_e32 v144, v118, v148
	v_mul_f32_e32 v152, v143, v163
	v_mul_f32_e32 v145, v144, v163
	v_fmac_f32_e32 v152, v144, v147
	v_mul_f32_e32 v144, v119, v148
	v_fma_f32 v145, v143, v147, -v145
	v_mul_f32_e32 v143, v127, v148
	v_mul_f32_e32 v153, v144, v164
	v_fma_f32 v153, v143, v161, -v153
	v_mul_f32_e32 v166, v143, v164
	v_mul_f32_e32 v143, v128, v148
	v_fmac_f32_e32 v166, v144, v161
	v_mul_f32_e32 v144, v120, v148
	v_mul_f32_e32 v168, v143, v165
	v_mul_f32_e32 v167, v144, v165
	v_fmac_f32_e32 v168, v144, v162
	v_mul_f32_e32 v144, v121, v148
	v_or_b32_e32 v142, s78, v150
	v_fma_f32 v167, v143, v162, -v167
	v_mul_f32_e32 v143, v129, v148
	v_mul_f32_e32 v169, v144, v155
	v_fma_f32 v169, v143, v154, -v169
	v_mul_f32_e32 v170, v143, v155
	v_mad_u64_u32 v[142:143], s[0:1], v142, s77, v[140:141]
	v_fmac_f32_e32 v170, v144, v154
	v_mad_i32_i24 v143, v151, s77, v143
	v_cvt_pk_bf16_f32 v144, v145, v153
	v_cvt_pk_bf16_f32 v145, v167, v169
	v_cvt_pk_bf16_f32 v152, v152, v166
	v_cvt_pk_bf16_f32 v153, v168, v170
	global_store_dwordx2 v[142:143], v[144:145], off offset:128
	global_store_dwordx2 v[142:143], v[152:153], off offset:160
	v_or_b32_e32 v144, s81, v150
	v_mov_b64_e32 v[142:143], s[24:25]
	v_mad_u64_u32 v[142:143], s[0:1], v144, s77, v[142:143]
	v_mul_f32_e32 v144, v122, v148
	v_mul_f32_e32 v145, v114, v148
	v_mul_f32_e32 v166, v145, v163
	v_mul_f32_e32 v163, v144, v163
	v_fma_f32 v166, v144, v147, -v166
	v_fmac_f32_e32 v163, v145, v147
	v_mul_f32_e32 v144, v123, v148
	v_mul_f32_e32 v145, v115, v148
	v_mul_f32_e32 v147, v145, v164
	v_mul_f32_e32 v164, v144, v164
	v_fma_f32 v147, v144, v161, -v147
	v_fmac_f32_e32 v164, v145, v161
	v_mul_f32_e32 v144, v124, v148
	v_mul_f32_e32 v145, v116, v148
	v_mul_f32_e32 v161, v145, v165
	v_mul_f32_e32 v165, v144, v165
	v_fma_f32 v161, v144, v162, -v161
	v_fmac_f32_e32 v165, v145, v162
	v_mul_f32_e32 v144, v125, v148
	v_mul_f32_e32 v145, v117, v148
	v_mad_i32_i24 v143, v151, s77, v143
	v_mul_f32_e32 v162, v145, v155
	v_mul_f32_e32 v155, v144, v155
	v_lshl_add_u64 v[152:153], v[142:143], 0, s[26:27]
	v_fmac_f32_e32 v155, v145, v154
	v_lshl_add_u64 v[142:143], v[142:143], 0, v[134:135]
	v_fma_f32 v162, v144, v154, -v162
	v_cvt_pk_bf16_f32 v144, v166, v147
	v_cvt_pk_bf16_f32 v145, v161, v162
	v_cvt_pk_bf16_f32 v154, v163, v164
	v_cvt_pk_bf16_f32 v155, v165, v155
	global_store_dwordx2 v[142:143], v[144:145], off offset:128

.LBB0_624:
	v_or_b32_e32 v122, 16, v146
	v_lshl_add_u64 v[114:115], v[152:153], 0, v[134:135]
	v_ashrrev_i32_e32 v123, 31, v122
	global_store_dwordx2 v[114:115], v[154:155], off offset:32
	v_lshlrev_b64 v[114:115], 5, v[122:123]
	v_lshl_add_u64 v[114:115], s[10:11], 0, v[114:115]
	v_mov_b32_e32 v114, v182
	v_mov_b32_e32 v115, v183
	v_mov_b32_e32 v116, v184
	v_mov_b32_e32 v117, v185
	v_cndmask_b32_e64 v118, 0, 1, s[38:39]
	v_cmp_ne_u32_e64 s[6:7], 1, v118
	s_andn2_b64 vcc, exec, s[38:39]
	s_mov_b64 s[8:9], -1
	v_add_f32_e32 v114, v114, v115
	v_add_f32_e32 v115, v116, v117
	v_add_f32_e32 v114, v114, v115
	v_fmamk_f32 v114, v114, 0x3b800000, v158
	v_rsq_f32_e32 v114, v114
	v_lshlrev_b64 v[116:117], 3, v[122:123]
	v_mul_f32_e32 v114, 0x3e16c740, v114
	s_cbranch_vccnz .LBB0_626
	v_mov_b32_e32 v118, v210
	v_mov_b32_e32 v119, v211
	v_mov_b32_e32 v120, v212
	v_mov_b32_e32 v121, v213
	v_and_b32_e32 v115, 0x1fdf, v122
	v_cvt_f32_u32_e32 v115, v115
	v_mul_f32_e32 v118, v118, v115
	v_mul_f32_e32 v122, v119, v115
	v_cvt_f64_f32_e32 v[118:119], v118
	v_mul_f32_e32 v123, v120, v115
	v_mul_f32_e32 v115, v121, v115
	v_cvt_f64_f32_e32 v[120:121], v122
	v_mul_f64 v[126:127], v[118:119], s[42:43]
	v_cvt_f64_f32_e32 v[122:123], v123
	v_mul_f64 v[128:129], v[120:121], s[42:43]
	v_rndne_f64_e32 v[126:127], v[126:127]
	v_mul_f64 v[142:143], v[122:123], s[42:43]
	v_rndne_f64_e32 v[128:129], v[128:129]
	v_fma_f64 v[118:119], v[118:119], s[42:43], -v[126:127]
	v_rndne_f64_e32 v[142:143], v[142:143]
	v_fma_f64 v[120:121], v[120:121], s[42:43], -v[128:129]
	v_mul_f64 v[118:119], v[118:119], s[44:45]
	v_fma_f64 v[122:123], v[122:123], s[42:43], -v[142:143]
	v_mul_f64 v[120:121], v[120:121], s[44:45]
	v_cvt_f32_f64_e32 v118, v[118:119]
	v_mul_f64 v[122:123], v[122:123], s[44:45]
	v_cvt_f32_f64_e32 v119, v[120:121]
	v_mul_f32_e32 v121, v118, v118
	v_cvt_f64_f32_e32 v[124:125], v115
	v_cvt_i32_f64_e32 v115, v[126:127]
	v_cvt_i32_f64_e32 v126, v[128:129]
	v_cvt_f32_f64_e32 v120, v[122:123]
	v_mul_f32_e32 v122, v119, v119
	v_fmamk_f32 v128, v121, 0x3638ef1d, v159
	v_fmamk_f32 v129, v121, 0xb493f27e, v160
	v_cvt_i32_f64_e32 v127, v[142:143]
	v_mul_f32_e32 v123, v120, v120
	v_fmamk_f32 v142, v122, 0x3638ef1d, v159
	v_fmamk_f32 v143, v122, 0xb493f27e, v160
	v_fmaak_f32 v128, v121, v128, 0x3c088888
	v_fmaak_f32 v129, v121, v129, 0xbab60b61
	v_fmamk_f32 v147, v123, 0x3638ef1d, v159
	v_fmamk_f32 v148, v123, 0xb493f27e, v160
	v_fmaak_f32 v142, v122, v142, 0x3c088888
	v_fmaak_f32 v143, v122, v143, 0xbab60b61
	v_fmaak_f32 v128, v121, v128, 0xbe2aaaab
	v_fmaak_f32 v129, v121, v129, 0x3d2aaaab
	v_and_b32_e32 v115, 3, v115
	v_fmaak_f32 v147, v123, v147, 0x3c088888
	v_fmaak_f32 v148, v123, v148, 0xbab60b61
	v_fmaak_f32 v142, v122, v142, 0xbe2aaaab
	v_fmaak_f32 v143, v122, v143, 0x3d2aaaab
	v_fma_f32 v128, v121, v128, 1.0
	v_fma_f32 v129, v121, v129, -0.5
	v_and_b32_e32 v126, 3, v126
	v_fmaak_f32 v147, v123, v147, 0xbe2aaaab
	v_fmaak_f32 v148, v123, v148, 0x3d2aaaab
	v_fma_f32 v142, v122, v142, 1.0
	v_fma_f32 v143, v122, v143, -0.5
	v_mul_f32_e32 v118, v128, v118
	v_fma_f32 v121, v121, v129, 1.0
	v_cmp_eq_u32_e32 vcc, 2, v115
	v_and_b32_e32 v127, 3, v127
	v_fma_f32 v147, v123, v147, 1.0
	v_fma_f32 v148, v123, v148, -0.5
	v_mul_f32_e32 v119, v142, v119
	v_fma_f32 v122, v122, v143, 1.0
	v_cndmask_b32_e64 v128, v118, -v121, vcc
	v_cndmask_b32_e32 v129, v121, v118, vcc
	v_cmp_eq_u32_e32 vcc, 2, v126
	v_mul_f32_e32 v120, v147, v120
	v_fma_f32 v123, v123, v148, 1.0
	v_cndmask_b32_e64 v142, v119, -v122, vcc
	v_cndmask_b32_e32 v143, v122, v119, vcc
	v_cmp_eq_u32_e32 vcc, 2, v127
	v_mul_f64 v[144:145], v[124:125], s[42:43]
	v_rndne_f64_e32 v[144:145], v[144:145]
	v_cndmask_b32_e64 v147, v120, -v123, vcc
	v_cndmask_b32_e32 v148, v123, v120, vcc
	v_cmp_eq_u32_e32 vcc, 1, v115
	v_fma_f64 v[124:125], v[124:125], s[42:43], -v[144:145]
	v_mul_f64 v[124:125], v[124:125], s[44:45]
	v_cndmask_b32_e64 v128, v128, -v118, vcc
	v_cndmask_b32_e64 v129, -v129, v121, vcc
	v_cmp_eq_u32_e32 vcc, 1, v126
	s_nop 1
	v_cndmask_b32_e64 v142, v142, -v119, vcc
	v_cndmask_b32_e64 v143, -v143, v122, vcc
	v_cmp_eq_u32_e32 vcc, 1, v127
	s_nop 1
	v_cndmask_b32_e64 v147, v147, -v120, vcc
	v_cndmask_b32_e64 v148, -v148, v123, vcc
	v_cmp_eq_u32_e32 vcc, 0, v115
	s_nop 1
	v_cndmask_b32_e32 v115, v128, v121, vcc
	v_cndmask_b32_e32 v128, v129, v118, vcc
	v_cmp_eq_u32_e32 vcc, 0, v126
	v_cvt_f32_f64_e32 v118, v[124:125]
	s_nop 0
	v_cndmask_b32_e32 v126, v142, v122, vcc
	v_cndmask_b32_e32 v129, v143, v119, vcc
	v_cmp_eq_u32_e32 vcc, 0, v127
	v_cvt_i32_f64_e32 v119, v[144:145]
	v_and_b32_e32 v119, 3, v119
	v_cndmask_b32_e32 v142, v148, v120, vcc
	v_mul_f32_e32 v120, v118, v118
	v_fmamk_f32 v121, v120, 0x3638ef1d, v159
	v_fmaak_f32 v121, v120, v121, 0x3c088888
	v_fmaak_f32 v121, v120, v121, 0xbe2aaaab
	v_fma_f32 v121, v120, v121, 1.0
	v_mul_f32_e32 v118, v121, v118
	v_fmamk_f32 v121, v120, 0xb493f27e, v160
	v_fmaak_f32 v121, v120, v121, 0xbab60b61
	v_fmaak_f32 v121, v120, v121, 0x3d2aaaab
	v_fma_f32 v121, v120, v121, -0.5
	v_cndmask_b32_e32 v127, v147, v123, vcc
	v_fma_f32 v120, v120, v121, 1.0
	v_cmp_eq_u32_e32 vcc, 2, v119
	v_cmp_eq_u32_e64 s[8:9], 1, v119
	s_nop 0
	v_cndmask_b32_e64 v121, v118, -v120, vcc
	v_cndmask_b32_e32 v122, v120, v118, vcc
	v_cndmask_b32_e64 v121, v121, -v118, s[8:9]
	v_cndmask_b32_e64 v122, -v122, v120, s[8:9]
	v_cmp_eq_u32_e32 vcc, 0, v119
	v_mul_f32_e32 v119, v110, v114
	s_mov_b64 s[8:9], 0
	v_cndmask_b32_e32 v124, v121, v120, vcc
	v_cndmask_b32_e32 v125, v122, v118, vcc
	v_mul_f32_e32 v120, v102, v114
	v_mul_f32_e32 v122, v119, v128
	v_mul_f32_e32 v121, v120, v128
	v_fmac_f32_e32 v122, v120, v115
	v_mul_f32_e32 v120, v103, v114
	v_fma_f32 v121, v119, v115, -v121
	v_mul_f32_e32 v119, v111, v114
	v_mul_f32_e32 v123, v120, v129
	v_fma_f32 v123, v119, v126, -v123
	v_mul_f32_e32 v143, v119, v129
	v_mul_f32_e32 v119, v112, v114
	v_fmac_f32_e32 v143, v120, v126
	v_mul_f32_e32 v120, v104, v114
	v_mul_f32_e32 v145, v119, v142
	v_mul_f32_e32 v144, v120, v142
	v_fmac_f32_e32 v145, v120, v127
	v_mul_f32_e32 v120, v105, v114
	v_or_b32_e32 v118, s78, v116
	v_fma_f32 v144, v119, v127, -v144
	v_mul_f32_e32 v119, v113, v114
	v_mul_f32_e32 v147, v120, v125
	v_fma_f32 v147, v119, v124, -v147
	v_mul_f32_e32 v148, v119, v125
	v_mad_u64_u32 v[118:119], s[0:1], v118, s77, v[140:141]
	v_fmac_f32_e32 v148, v120, v124
	v_mad_i32_i24 v119, v117, s77, v119
	v_cvt_pk_bf16_f32 v120, v121, v123
	v_cvt_pk_bf16_f32 v121, v144, v147
	v_cvt_pk_bf16_f32 v122, v122, v143
	v_cvt_pk_bf16_f32 v123, v145, v148
	global_store_dwordx2 v[118:119], v[120:121], off offset:128
	global_store_dwordx2 v[118:119], v[122:123], off offset:160
	v_mul_f32_e32 v123, v98, v114
	v_mul_f32_e32 v122, v106, v114
	v_mul_f32_e32 v143, v123, v128
	v_fma_f32 v143, v122, v115, -v143
	v_mul_f32_e32 v128, v122, v128
	v_mul_f32_e32 v122, v99, v114
	v_fmac_f32_e32 v128, v123, v115
	v_mul_f32_e32 v115, v107, v114
	v_mul_f32_e32 v123, v122, v129
	v_fma_f32 v144, v115, v126, -v123
	v_mul_f32_e32 v115, v115, v129
	v_fmac_f32_e32 v115, v122, v126
	v_mul_f32_e32 v122, v108, v114
	v_mul_f32_e32 v123, v100, v114
	v_or_b32_e32 v120, s81, v116
	v_mov_b64_e32 v[118:119], s[24:25]
	v_mul_f32_e32 v126, v123, v142
	v_mul_f32_e32 v129, v122, v142
	v_mad_u64_u32 v[120:121], s[0:1], v120, s77, v[118:119]
	v_fma_f32 v126, v122, v127, -v126
	v_fmac_f32_e32 v129, v123, v127
	v_mul_f32_e32 v122, v109, v114
	v_mul_f32_e32 v123, v101, v114
	v_mad_i32_i24 v121, v117, s77, v121
	v_mul_f32_e32 v127, v123, v125
	v_mul_f32_e32 v142, v122, v125
	v_lshl_add_u64 v[118:119], v[120:121], 0, s[26:27]
	v_fma_f32 v127, v122, v124, -v127
	v_fmac_f32_e32 v142, v123, v124
	v_lshl_add_u64 v[122:123], v[120:121], 0, v[134:135]
	v_cvt_pk_bf16_f32 v124, v143, v144
	v_cvt_pk_bf16_f32 v125, v126, v127
	v_cvt_pk_bf16_f32 v120, v128, v115
	v_cvt_pk_bf16_f32 v121, v129, v142
	global_store_dwordx2 v[122:123], v[124:125], off offset:128

.LBB0_628:
	v_or_b32_e32 v106, 32, v146
	v_lshl_add_u64 v[98:99], v[118:119], 0, v[134:135]
	v_ashrrev_i32_e32 v107, 31, v106
	global_store_dwordx2 v[98:99], v[120:121], off offset:32
	v_lshlrev_b64 v[98:99], 5, v[106:107]
	v_lshl_add_u64 v[98:99], s[10:11], 0, v[98:99]
	v_mov_b32_e32 v98, v186
	v_mov_b32_e32 v99, v187
	v_mov_b32_e32 v100, v188
	v_mov_b32_e32 v101, v189
	s_and_b64 vcc, exec, s[6:7]
	s_mov_b64 s[8:9], -1
	v_add_f32_e32 v98, v98, v99
	v_add_f32_e32 v99, v100, v101
	v_add_f32_e32 v98, v98, v99
	v_fmamk_f32 v98, v98, 0x3b800000, v158
	v_rsq_f32_e32 v98, v98
	v_lshlrev_b64 v[100:101], 3, v[106:107]
	v_mul_f32_e32 v98, 0x3e16c740, v98
	s_cbranch_vccnz .LBB0_630
	v_mov_b32_e32 v102, v210
	v_mov_b32_e32 v103, v211
	v_mov_b32_e32 v104, v212
	v_mov_b32_e32 v105, v213
	v_and_b32_e32 v99, 0x1fef, v106
	v_cvt_f32_u32_e32 v99, v99
	v_mul_f32_e32 v102, v102, v99
	v_mul_f32_e32 v106, v103, v99
	v_cvt_f64_f32_e32 v[102:103], v102
	v_mul_f32_e32 v107, v104, v99
	v_mul_f32_e32 v99, v105, v99
	v_cvt_f64_f32_e32 v[104:105], v106
	v_mul_f64 v[110:111], v[102:103], s[42:43]
	v_cvt_f64_f32_e32 v[106:107], v107
	v_mul_f64 v[112:113], v[104:105], s[42:43]
	v_rndne_f64_e32 v[110:111], v[110:111]
	v_mul_f64 v[114:115], v[106:107], s[42:43]
	v_rndne_f64_e32 v[112:113], v[112:113]
	v_fma_f64 v[102:103], v[102:103], s[42:43], -v[110:111]
	v_rndne_f64_e32 v[114:115], v[114:115]
	v_fma_f64 v[104:105], v[104:105], s[42:43], -v[112:113]
	v_mul_f64 v[102:103], v[102:103], s[44:45]
	v_fma_f64 v[106:107], v[106:107], s[42:43], -v[114:115]
	v_mul_f64 v[104:105], v[104:105], s[44:45]
	v_cvt_f32_f64_e32 v102, v[102:103]
	v_mul_f64 v[106:107], v[106:107], s[44:45]
	v_cvt_f32_f64_e32 v103, v[104:105]
	v_mul_f32_e32 v105, v102, v102
	v_cvt_f64_f32_e32 v[108:109], v99
	v_cvt_i32_f64_e32 v99, v[110:111]
	v_cvt_i32_f64_e32 v110, v[112:113]
	v_cvt_f32_f64_e32 v104, v[106:107]
	v_mul_f32_e32 v106, v103, v103
	v_fmamk_f32 v112, v105, 0x3638ef1d, v159
	v_fmamk_f32 v113, v105, 0xb493f27e, v160
	v_cvt_i32_f64_e32 v111, v[114:115]
	v_mul_f32_e32 v107, v104, v104
	v_fmamk_f32 v114, v106, 0x3638ef1d, v159
	v_fmamk_f32 v115, v106, 0xb493f27e, v160
	v_fmaak_f32 v112, v105, v112, 0x3c088888
	v_fmaak_f32 v113, v105, v113, 0xbab60b61
	v_fmamk_f32 v118, v107, 0x3638ef1d, v159
	v_fmamk_f32 v119, v107, 0xb493f27e, v160
	v_fmaak_f32 v114, v106, v114, 0x3c088888
	v_fmaak_f32 v115, v106, v115, 0xbab60b61
	v_fmaak_f32 v112, v105, v112, 0xbe2aaaab
	v_fmaak_f32 v113, v105, v113, 0x3d2aaaab
	v_and_b32_e32 v99, 3, v99
	v_fmaak_f32 v118, v107, v118, 0x3c088888
	v_fmaak_f32 v119, v107, v119, 0xbab60b61
	v_fmaak_f32 v114, v106, v114, 0xbe2aaaab
	v_fmaak_f32 v115, v106, v115, 0x3d2aaaab
	v_fma_f32 v112, v105, v112, 1.0
	v_fma_f32 v113, v105, v113, -0.5
	v_and_b32_e32 v110, 3, v110
	v_fmaak_f32 v118, v107, v118, 0xbe2aaaab
	v_fmaak_f32 v119, v107, v119, 0x3d2aaaab
	v_fma_f32 v114, v106, v114, 1.0
	v_fma_f32 v115, v106, v115, -0.5
	v_mul_f32_e32 v102, v112, v102
	v_fma_f32 v105, v105, v113, 1.0
	v_cmp_eq_u32_e32 vcc, 2, v99
	v_and_b32_e32 v111, 3, v111
	v_fma_f32 v118, v107, v118, 1.0
	v_fma_f32 v119, v107, v119, -0.5
	v_mul_f32_e32 v103, v114, v103
	v_fma_f32 v106, v106, v115, 1.0
	v_cndmask_b32_e64 v112, v102, -v105, vcc
	v_cndmask_b32_e32 v113, v105, v102, vcc
	v_cmp_eq_u32_e32 vcc, 2, v110
	v_mul_f32_e32 v104, v118, v104
	v_fma_f32 v107, v107, v119, 1.0
	v_cndmask_b32_e64 v114, v103, -v106, vcc
	v_cndmask_b32_e32 v115, v106, v103, vcc
	v_cmp_eq_u32_e32 vcc, 2, v111
	v_mul_f64 v[116:117], v[108:109], s[42:43]
	v_rndne_f64_e32 v[116:117], v[116:117]
	v_cndmask_b32_e64 v118, v104, -v107, vcc
	v_cndmask_b32_e32 v119, v107, v104, vcc
	v_cmp_eq_u32_e32 vcc, 1, v99
	v_fma_f64 v[108:109], v[108:109], s[42:43], -v[116:117]
	v_mul_f64 v[108:109], v[108:109], s[44:45]
	v_cndmask_b32_e64 v112, v112, -v102, vcc
	v_cndmask_b32_e64 v113, -v113, v105, vcc
	v_cmp_eq_u32_e32 vcc, 1, v110
	s_nop 1
	v_cndmask_b32_e64 v114, v114, -v103, vcc
	v_cndmask_b32_e64 v115, -v115, v106, vcc
	v_cmp_eq_u32_e32 vcc, 1, v111
	s_nop 1
	v_cndmask_b32_e64 v118, v118, -v104, vcc
	v_cndmask_b32_e64 v119, -v119, v107, vcc
	v_cmp_eq_u32_e32 vcc, 0, v99
	s_nop 1
	v_cndmask_b32_e32 v99, v112, v105, vcc
	v_cndmask_b32_e32 v112, v113, v102, vcc
	v_cmp_eq_u32_e32 vcc, 0, v110
	v_cvt_f32_f64_e32 v102, v[108:109]
	s_nop 0
	v_cndmask_b32_e32 v110, v114, v106, vcc
	v_cndmask_b32_e32 v113, v115, v103, vcc
	v_cmp_eq_u32_e32 vcc, 0, v111
	v_cvt_i32_f64_e32 v103, v[116:117]
	v_and_b32_e32 v103, 3, v103
	v_cndmask_b32_e32 v114, v119, v104, vcc
	v_mul_f32_e32 v104, v102, v102
	v_fmamk_f32 v105, v104, 0x3638ef1d, v159
	v_fmaak_f32 v105, v104, v105, 0x3c088888
	v_fmaak_f32 v105, v104, v105, 0xbe2aaaab
	v_fma_f32 v105, v104, v105, 1.0
	v_mul_f32_e32 v102, v105, v102
	v_fmamk_f32 v105, v104, 0xb493f27e, v160
	v_fmaak_f32 v105, v104, v105, 0xbab60b61
	v_fmaak_f32 v105, v104, v105, 0x3d2aaaab
	v_fma_f32 v105, v104, v105, -0.5
	v_cndmask_b32_e32 v111, v118, v107, vcc
	v_fma_f32 v104, v104, v105, 1.0
	v_cmp_eq_u32_e32 vcc, 2, v103
	v_cmp_eq_u32_e64 s[8:9], 1, v103
	s_nop 0
	v_cndmask_b32_e64 v105, v102, -v104, vcc
	v_cndmask_b32_e32 v106, v104, v102, vcc
	v_cndmask_b32_e64 v105, v105, -v102, s[8:9]
	v_cndmask_b32_e64 v106, -v106, v104, s[8:9]
	v_cmp_eq_u32_e32 vcc, 0, v103
	v_mul_f32_e32 v103, v94, v98
	s_mov_b64 s[8:9], 0
	v_cndmask_b32_e32 v108, v105, v104, vcc
	v_cndmask_b32_e32 v109, v106, v102, vcc
	v_mul_f32_e32 v104, v86, v98
	v_mul_f32_e32 v106, v103, v112
	v_mul_f32_e32 v105, v104, v112
	v_fmac_f32_e32 v106, v104, v99
	v_mul_f32_e32 v104, v87, v98
	v_fma_f32 v105, v103, v99, -v105
	v_mul_f32_e32 v103, v95, v98
	v_mul_f32_e32 v107, v104, v113
	v_fma_f32 v107, v103, v110, -v107
	v_mul_f32_e32 v115, v103, v113
	v_mul_f32_e32 v103, v96, v98
	v_fmac_f32_e32 v115, v104, v110
	v_mul_f32_e32 v104, v88, v98
	v_mul_f32_e32 v117, v103, v114
	v_mul_f32_e32 v116, v104, v114
	v_fmac_f32_e32 v117, v104, v111
	v_mul_f32_e32 v104, v89, v98
	v_or_b32_e32 v102, s78, v100
	v_fma_f32 v116, v103, v111, -v116
	v_mul_f32_e32 v103, v97, v98
	v_mul_f32_e32 v118, v104, v109
	v_fma_f32 v118, v103, v108, -v118
	v_mul_f32_e32 v119, v103, v109
	v_mad_u64_u32 v[102:103], s[0:1], v102, s77, v[140:141]
	v_fmac_f32_e32 v119, v104, v108
	v_mad_i32_i24 v103, v101, s77, v103
	v_cvt_pk_bf16_f32 v104, v105, v107
	v_cvt_pk_bf16_f32 v105, v116, v118
	v_cvt_pk_bf16_f32 v106, v106, v115
	v_cvt_pk_bf16_f32 v107, v117, v119
	global_store_dwordx2 v[102:103], v[104:105], off offset:128
	global_store_dwordx2 v[102:103], v[106:107], off offset:160
	v_mul_f32_e32 v107, v82, v98
	v_mul_f32_e32 v106, v90, v98
	v_mul_f32_e32 v115, v107, v112
	v_fma_f32 v115, v106, v99, -v115
	v_mul_f32_e32 v112, v106, v112
	v_mul_f32_e32 v106, v83, v98
	v_fmac_f32_e32 v112, v107, v99
	v_mul_f32_e32 v99, v91, v98
	v_mul_f32_e32 v107, v106, v113
	v_fma_f32 v116, v99, v110, -v107
	v_mul_f32_e32 v99, v99, v113
	v_fmac_f32_e32 v99, v106, v110
	v_mul_f32_e32 v106, v92, v98
	v_mul_f32_e32 v107, v84, v98
	v_or_b32_e32 v104, s81, v100
	v_mov_b64_e32 v[102:103], s[24:25]
	v_mul_f32_e32 v110, v107, v114
	v_mul_f32_e32 v113, v106, v114
	v_mad_u64_u32 v[104:105], s[0:1], v104, s77, v[102:103]
	v_fma_f32 v110, v106, v111, -v110
	v_fmac_f32_e32 v113, v107, v111
	v_mul_f32_e32 v106, v93, v98
	v_mul_f32_e32 v107, v85, v98
	v_mad_i32_i24 v105, v101, s77, v105
	v_mul_f32_e32 v111, v107, v109
	v_mul_f32_e32 v114, v106, v109
	v_lshl_add_u64 v[102:103], v[104:105], 0, s[26:27]
	v_fma_f32 v111, v106, v108, -v111
	v_fmac_f32_e32 v114, v107, v108
	v_lshl_add_u64 v[106:107], v[104:105], 0, v[134:135]
	v_cvt_pk_bf16_f32 v108, v115, v116
	v_cvt_pk_bf16_f32 v109, v110, v111
	v_cvt_pk_bf16_f32 v104, v112, v99
	v_cvt_pk_bf16_f32 v105, v113, v114
	global_store_dwordx2 v[106:107], v[108:109], off offset:128

.LBB0_632:
	v_or_b32_e32 v90, 48, v146
	v_lshl_add_u64 v[82:83], v[102:103], 0, v[134:135]
	v_ashrrev_i32_e32 v91, 31, v90
	global_store_dwordx2 v[82:83], v[104:105], off offset:32
	v_lshlrev_b64 v[82:83], 5, v[90:91]
	v_lshl_add_u64 v[82:83], s[10:11], 0, v[82:83]
	v_mov_b32_e32 v82, v190
	v_mov_b32_e32 v83, v191
	v_mov_b32_e32 v84, v192
	v_mov_b32_e32 v85, v193
	s_and_b64 vcc, exec, s[6:7]
	s_mov_b64 s[8:9], -1
	v_add_f32_e32 v82, v82, v83
	v_add_f32_e32 v83, v84, v85
	v_add_f32_e32 v82, v82, v83
	v_fmamk_f32 v82, v82, 0x3b800000, v158
	v_rsq_f32_e32 v82, v82
	v_lshlrev_b64 v[84:85], 3, v[90:91]
	v_mul_f32_e32 v82, 0x3e16c740, v82
	s_cbranch_vccnz .LBB0_634
	v_mov_b32_e32 v86, v210
	v_mov_b32_e32 v87, v211
	v_mov_b32_e32 v88, v212
	v_mov_b32_e32 v89, v213
	v_and_b32_e32 v83, 0x1fff, v90
	v_cvt_f32_u32_e32 v83, v83
	v_mul_f32_e32 v86, v86, v83
	v_mul_f32_e32 v90, v87, v83
	v_cvt_f64_f32_e32 v[86:87], v86
	v_mul_f32_e32 v91, v88, v83
	v_mul_f32_e32 v83, v89, v83
	v_cvt_f64_f32_e32 v[88:89], v90
	v_mul_f64 v[94:95], v[86:87], s[42:43]
	v_cvt_f64_f32_e32 v[90:91], v91
	v_mul_f64 v[96:97], v[88:89], s[42:43]
	v_rndne_f64_e32 v[94:95], v[94:95]
	v_mul_f64 v[98:99], v[90:91], s[42:43]
	v_rndne_f64_e32 v[96:97], v[96:97]
	v_fma_f64 v[86:87], v[86:87], s[42:43], -v[94:95]
	v_rndne_f64_e32 v[98:99], v[98:99]
	v_fma_f64 v[88:89], v[88:89], s[42:43], -v[96:97]
	v_mul_f64 v[86:87], v[86:87], s[44:45]
	v_fma_f64 v[90:91], v[90:91], s[42:43], -v[98:99]
	v_mul_f64 v[88:89], v[88:89], s[44:45]
	v_cvt_f32_f64_e32 v86, v[86:87]
	v_mul_f64 v[90:91], v[90:91], s[44:45]
	v_cvt_f32_f64_e32 v87, v[88:89]
	v_mul_f32_e32 v89, v86, v86
	v_cvt_f64_f32_e32 v[92:93], v83
	v_cvt_i32_f64_e32 v83, v[94:95]
	v_cvt_i32_f64_e32 v94, v[96:97]
	v_cvt_f32_f64_e32 v88, v[90:91]
	v_mul_f32_e32 v90, v87, v87
	v_fmamk_f32 v96, v89, 0x3638ef1d, v159
	v_fmamk_f32 v97, v89, 0xb493f27e, v160
	v_cvt_i32_f64_e32 v95, v[98:99]
	v_mul_f32_e32 v91, v88, v88
	v_fmamk_f32 v98, v90, 0x3638ef1d, v159
	v_fmamk_f32 v99, v90, 0xb493f27e, v160
	v_fmaak_f32 v96, v89, v96, 0x3c088888
	v_fmaak_f32 v97, v89, v97, 0xbab60b61
	v_fmamk_f32 v102, v91, 0x3638ef1d, v159
	v_fmamk_f32 v103, v91, 0xb493f27e, v160
	v_fmaak_f32 v98, v90, v98, 0x3c088888
	v_fmaak_f32 v99, v90, v99, 0xbab60b61
	v_fmaak_f32 v96, v89, v96, 0xbe2aaaab
	v_fmaak_f32 v97, v89, v97, 0x3d2aaaab
	v_and_b32_e32 v83, 3, v83
	v_fmaak_f32 v102, v91, v102, 0x3c088888
	v_fmaak_f32 v103, v91, v103, 0xbab60b61
	v_fmaak_f32 v98, v90, v98, 0xbe2aaaab
	v_fmaak_f32 v99, v90, v99, 0x3d2aaaab
	v_fma_f32 v96, v89, v96, 1.0
	v_fma_f32 v97, v89, v97, -0.5
	v_and_b32_e32 v94, 3, v94
	v_fmaak_f32 v102, v91, v102, 0xbe2aaaab
	v_fmaak_f32 v103, v91, v103, 0x3d2aaaab
	v_fma_f32 v98, v90, v98, 1.0
	v_fma_f32 v99, v90, v99, -0.5
	v_mul_f32_e32 v86, v96, v86
	v_fma_f32 v89, v89, v97, 1.0
	v_cmp_eq_u32_e32 vcc, 2, v83
	v_and_b32_e32 v95, 3, v95
	v_fma_f32 v102, v91, v102, 1.0
	v_fma_f32 v103, v91, v103, -0.5
	v_mul_f32_e32 v87, v98, v87
	v_fma_f32 v90, v90, v99, 1.0
	v_cndmask_b32_e64 v96, v86, -v89, vcc
	v_cndmask_b32_e32 v97, v89, v86, vcc
	v_cmp_eq_u32_e32 vcc, 2, v94
	v_mul_f32_e32 v88, v102, v88
	v_fma_f32 v91, v91, v103, 1.0
	v_cndmask_b32_e64 v98, v87, -v90, vcc
	v_cndmask_b32_e32 v99, v90, v87, vcc
	v_cmp_eq_u32_e32 vcc, 2, v95
	v_mul_f64 v[100:101], v[92:93], s[42:43]
	v_rndne_f64_e32 v[100:101], v[100:101]
	v_cndmask_b32_e64 v102, v88, -v91, vcc
	v_cndmask_b32_e32 v103, v91, v88, vcc
	v_cmp_eq_u32_e32 vcc, 1, v83
	v_fma_f64 v[92:93], v[92:93], s[42:43], -v[100:101]
	v_mul_f64 v[92:93], v[92:93], s[44:45]
	v_cndmask_b32_e64 v96, v96, -v86, vcc
	v_cndmask_b32_e64 v97, -v97, v89, vcc
	v_cmp_eq_u32_e32 vcc, 1, v94
	s_nop 1
	v_cndmask_b32_e64 v98, v98, -v87, vcc
	v_cndmask_b32_e64 v99, -v99, v90, vcc
	v_cmp_eq_u32_e32 vcc, 1, v95
	s_nop 1
	v_cndmask_b32_e64 v102, v102, -v88, vcc
	v_cndmask_b32_e64 v103, -v103, v91, vcc
	v_cmp_eq_u32_e32 vcc, 0, v83
	s_nop 1
	v_cndmask_b32_e32 v83, v96, v89, vcc
	v_cndmask_b32_e32 v96, v97, v86, vcc
	v_cmp_eq_u32_e32 vcc, 0, v94
	v_cvt_f32_f64_e32 v86, v[92:93]
	s_nop 0
	v_cndmask_b32_e32 v94, v98, v90, vcc
	v_cndmask_b32_e32 v97, v99, v87, vcc
	v_cmp_eq_u32_e32 vcc, 0, v95
	v_cvt_i32_f64_e32 v87, v[100:101]
	v_and_b32_e32 v87, 3, v87
	v_cndmask_b32_e32 v98, v103, v88, vcc
	v_mul_f32_e32 v88, v86, v86
	v_fmamk_f32 v89, v88, 0x3638ef1d, v159
	v_fmaak_f32 v89, v88, v89, 0x3c088888
	v_fmaak_f32 v89, v88, v89, 0xbe2aaaab
	v_fma_f32 v89, v88, v89, 1.0
	v_mul_f32_e32 v86, v89, v86
	v_fmamk_f32 v89, v88, 0xb493f27e, v160
	v_fmaak_f32 v89, v88, v89, 0xbab60b61
	v_fmaak_f32 v89, v88, v89, 0x3d2aaaab
	v_fma_f32 v89, v88, v89, -0.5
	v_cndmask_b32_e32 v95, v102, v91, vcc
	v_fma_f32 v88, v88, v89, 1.0
	v_cmp_eq_u32_e32 vcc, 2, v87
	v_cmp_eq_u32_e64 s[8:9], 1, v87
	s_nop 0
	v_cndmask_b32_e64 v89, v86, -v88, vcc
	v_cndmask_b32_e32 v90, v88, v86, vcc
	v_cndmask_b32_e64 v89, v89, -v86, s[8:9]
	v_cndmask_b32_e64 v90, -v90, v88, s[8:9]
	v_cmp_eq_u32_e32 vcc, 0, v87
	v_mul_f32_e32 v87, v78, v82
	s_mov_b64 s[8:9], 0
	v_cndmask_b32_e32 v92, v89, v88, vcc
	v_cndmask_b32_e32 v93, v90, v86, vcc
	v_mul_f32_e32 v88, v70, v82
	v_mul_f32_e32 v90, v87, v96
	v_mul_f32_e32 v89, v88, v96
	v_fmac_f32_e32 v90, v88, v83
	v_mul_f32_e32 v88, v71, v82
	v_fma_f32 v89, v87, v83, -v89
	v_mul_f32_e32 v87, v79, v82
	v_mul_f32_e32 v91, v88, v97
	v_fma_f32 v91, v87, v94, -v91
	v_mul_f32_e32 v99, v87, v97
	v_mul_f32_e32 v87, v80, v82
	v_fmac_f32_e32 v99, v88, v94
	v_mul_f32_e32 v88, v72, v82
	v_mul_f32_e32 v101, v87, v98
	v_mul_f32_e32 v100, v88, v98
	v_fmac_f32_e32 v101, v88, v95
	v_mul_f32_e32 v88, v73, v82
	v_or_b32_e32 v86, s78, v84
	v_fma_f32 v100, v87, v95, -v100
	v_mul_f32_e32 v87, v81, v82
	v_mul_f32_e32 v102, v88, v93
	v_fma_f32 v102, v87, v92, -v102
	v_mul_f32_e32 v103, v87, v93
	v_mad_u64_u32 v[86:87], s[0:1], v86, s77, v[140:141]
	v_fmac_f32_e32 v103, v88, v92
	v_mad_i32_i24 v87, v85, s77, v87
	v_cvt_pk_bf16_f32 v88, v89, v91
	v_cvt_pk_bf16_f32 v89, v100, v102
	v_cvt_pk_bf16_f32 v90, v90, v99
	v_cvt_pk_bf16_f32 v91, v101, v103
	global_store_dwordx2 v[86:87], v[88:89], off offset:128
	global_store_dwordx2 v[86:87], v[90:91], off offset:160
	v_mul_f32_e32 v91, v66, v82
	v_mul_f32_e32 v90, v74, v82
	v_mul_f32_e32 v99, v91, v96
	v_fma_f32 v99, v90, v83, -v99
	v_mul_f32_e32 v96, v90, v96
	v_mul_f32_e32 v90, v67, v82
	v_fmac_f32_e32 v96, v91, v83
	v_mul_f32_e32 v83, v75, v82
	v_mul_f32_e32 v91, v90, v97
	v_fma_f32 v100, v83, v94, -v91
	v_mul_f32_e32 v83, v83, v97
	v_fmac_f32_e32 v83, v90, v94
	v_mul_f32_e32 v90, v76, v82
	v_mul_f32_e32 v91, v68, v82
	v_or_b32_e32 v88, s81, v84
	v_mov_b64_e32 v[86:87], s[24:25]
	v_mul_f32_e32 v94, v91, v98
	v_mul_f32_e32 v97, v90, v98
	v_mad_u64_u32 v[88:89], s[0:1], v88, s77, v[86:87]
	v_fma_f32 v94, v90, v95, -v94
	v_fmac_f32_e32 v97, v91, v95
	v_mul_f32_e32 v90, v77, v82
	v_mul_f32_e32 v91, v69, v82
	v_mad_i32_i24 v89, v85, s77, v89
	v_mul_f32_e32 v95, v91, v93
	v_mul_f32_e32 v98, v90, v93
	v_lshl_add_u64 v[86:87], v[88:89], 0, s[26:27]
	v_fma_f32 v95, v90, v92, -v95
	v_fmac_f32_e32 v98, v91, v92
	v_lshl_add_u64 v[90:91], v[88:89], 0, v[134:135]
	v_cvt_pk_bf16_f32 v92, v99, v100
	v_cvt_pk_bf16_f32 v93, v94, v95
	v_cvt_pk_bf16_f32 v88, v96, v83
	v_cvt_pk_bf16_f32 v89, v97, v98
	global_store_dwordx2 v[90:91], v[92:93], off offset:128

.LBB0_636:
	v_add_u32_e32 v74, 0x80, v146
	v_lshl_add_u64 v[66:67], v[86:87], 0, v[134:135]
	v_ashrrev_i32_e32 v75, 31, v74
	global_store_dwordx2 v[66:67], v[88:89], off offset:32
	v_lshlrev_b64 v[66:67], 5, v[74:75]
	v_lshl_add_u64 v[66:67], s[10:11], 0, v[66:67]
	v_mov_b32_e32 v66, v194
	v_mov_b32_e32 v67, v195
	v_mov_b32_e32 v68, v196
	v_mov_b32_e32 v69, v197
	s_and_b64 vcc, exec, s[6:7]
	s_mov_b64 s[8:9], -1
	v_add_f32_e32 v66, v66, v67
	v_add_f32_e32 v67, v68, v69
	v_add_f32_e32 v66, v66, v67
	v_fmamk_f32 v66, v66, 0x3b800000, v158
	v_rsq_f32_e32 v66, v66
	v_lshlrev_b64 v[68:69], 3, v[74:75]
	v_mul_f32_e32 v66, 0x3e16c740, v66
	s_cbranch_vccnz .LBB0_638
	v_mov_b32_e32 v70, v210
	v_mov_b32_e32 v71, v211
	v_mov_b32_e32 v72, v212
	v_mov_b32_e32 v73, v213
	v_and_b32_e32 v67, 0x1fcf, v74
	v_cvt_f32_u32_e32 v67, v67
	v_mul_f32_e32 v70, v70, v67
	v_mul_f32_e32 v74, v71, v67
	v_cvt_f64_f32_e32 v[70:71], v70
	v_mul_f32_e32 v75, v72, v67
	v_mul_f32_e32 v67, v73, v67
	v_cvt_f64_f32_e32 v[72:73], v74
	v_mul_f64 v[78:79], v[70:71], s[42:43]
	v_cvt_f64_f32_e32 v[74:75], v75
	v_mul_f64 v[80:81], v[72:73], s[42:43]
	v_rndne_f64_e32 v[78:79], v[78:79]
	v_mul_f64 v[82:83], v[74:75], s[42:43]
	v_rndne_f64_e32 v[80:81], v[80:81]
	v_fma_f64 v[70:71], v[70:71], s[42:43], -v[78:79]
	v_rndne_f64_e32 v[82:83], v[82:83]
	v_fma_f64 v[72:73], v[72:73], s[42:43], -v[80:81]
	v_mul_f64 v[70:71], v[70:71], s[44:45]
	v_fma_f64 v[74:75], v[74:75], s[42:43], -v[82:83]
	v_mul_f64 v[72:73], v[72:73], s[44:45]
	v_cvt_f32_f64_e32 v70, v[70:71]
	v_mul_f64 v[74:75], v[74:75], s[44:45]
	v_cvt_f32_f64_e32 v71, v[72:73]
	v_mul_f32_e32 v73, v70, v70
	v_cvt_f64_f32_e32 v[76:77], v67
	v_cvt_i32_f64_e32 v67, v[78:79]
	v_cvt_i32_f64_e32 v78, v[80:81]
	v_cvt_f32_f64_e32 v72, v[74:75]
	v_mul_f32_e32 v74, v71, v71
	v_fmamk_f32 v80, v73, 0x3638ef1d, v159
	v_fmamk_f32 v81, v73, 0xb493f27e, v160
	v_cvt_i32_f64_e32 v79, v[82:83]
	v_mul_f32_e32 v75, v72, v72
	v_fmamk_f32 v82, v74, 0x3638ef1d, v159
	v_fmamk_f32 v83, v74, 0xb493f27e, v160
	v_fmaak_f32 v80, v73, v80, 0x3c088888
	v_fmaak_f32 v81, v73, v81, 0xbab60b61
	v_fmamk_f32 v86, v75, 0x3638ef1d, v159
	v_fmamk_f32 v87, v75, 0xb493f27e, v160
	v_fmaak_f32 v82, v74, v82, 0x3c088888
	v_fmaak_f32 v83, v74, v83, 0xbab60b61
	v_fmaak_f32 v80, v73, v80, 0xbe2aaaab
	v_fmaak_f32 v81, v73, v81, 0x3d2aaaab
	v_and_b32_e32 v67, 3, v67
	v_fmaak_f32 v86, v75, v86, 0x3c088888
	v_fmaak_f32 v87, v75, v87, 0xbab60b61
	v_fmaak_f32 v82, v74, v82, 0xbe2aaaab
	v_fmaak_f32 v83, v74, v83, 0x3d2aaaab
	v_fma_f32 v80, v73, v80, 1.0
	v_fma_f32 v81, v73, v81, -0.5
	v_and_b32_e32 v78, 3, v78
	v_fmaak_f32 v86, v75, v86, 0xbe2aaaab
	v_fmaak_f32 v87, v75, v87, 0x3d2aaaab
	v_fma_f32 v82, v74, v82, 1.0
	v_fma_f32 v83, v74, v83, -0.5
	v_mul_f32_e32 v70, v80, v70
	v_fma_f32 v73, v73, v81, 1.0
	v_cmp_eq_u32_e32 vcc, 2, v67
	v_and_b32_e32 v79, 3, v79
	v_fma_f32 v86, v75, v86, 1.0
	v_fma_f32 v87, v75, v87, -0.5
	v_mul_f32_e32 v71, v82, v71
	v_fma_f32 v74, v74, v83, 1.0
	v_cndmask_b32_e64 v80, v70, -v73, vcc
	v_cndmask_b32_e32 v81, v73, v70, vcc
	v_cmp_eq_u32_e32 vcc, 2, v78
	v_mul_f32_e32 v72, v86, v72
	v_fma_f32 v75, v75, v87, 1.0
	v_cndmask_b32_e64 v82, v71, -v74, vcc
	v_cndmask_b32_e32 v83, v74, v71, vcc
	v_cmp_eq_u32_e32 vcc, 2, v79
	v_mul_f64 v[84:85], v[76:77], s[42:43]
	v_rndne_f64_e32 v[84:85], v[84:85]
	v_cndmask_b32_e64 v86, v72, -v75, vcc
	v_cndmask_b32_e32 v87, v75, v72, vcc
	v_cmp_eq_u32_e32 vcc, 1, v67
	v_fma_f64 v[76:77], v[76:77], s[42:43], -v[84:85]
	v_mul_f64 v[76:77], v[76:77], s[44:45]
	v_cndmask_b32_e64 v80, v80, -v70, vcc
	v_cndmask_b32_e64 v81, -v81, v73, vcc
	v_cmp_eq_u32_e32 vcc, 1, v78
	s_nop 1
	v_cndmask_b32_e64 v82, v82, -v71, vcc
	v_cndmask_b32_e64 v83, -v83, v74, vcc
	v_cmp_eq_u32_e32 vcc, 1, v79
	s_nop 1
	v_cndmask_b32_e64 v86, v86, -v72, vcc
	v_cndmask_b32_e64 v87, -v87, v75, vcc
	v_cmp_eq_u32_e32 vcc, 0, v67
	s_nop 1
	v_cndmask_b32_e32 v67, v80, v73, vcc
	v_cndmask_b32_e32 v80, v81, v70, vcc
	v_cmp_eq_u32_e32 vcc, 0, v78
	v_cvt_f32_f64_e32 v70, v[76:77]
	s_nop 0
	v_cndmask_b32_e32 v78, v82, v74, vcc
	v_cndmask_b32_e32 v81, v83, v71, vcc
	v_cmp_eq_u32_e32 vcc, 0, v79
	v_cvt_i32_f64_e32 v71, v[84:85]
	v_and_b32_e32 v71, 3, v71
	v_cndmask_b32_e32 v82, v87, v72, vcc
	v_mul_f32_e32 v72, v70, v70
	v_fmamk_f32 v73, v72, 0x3638ef1d, v159
	v_fmaak_f32 v73, v72, v73, 0x3c088888
	v_fmaak_f32 v73, v72, v73, 0xbe2aaaab
	v_fma_f32 v73, v72, v73, 1.0
	v_mul_f32_e32 v70, v73, v70
	v_fmamk_f32 v73, v72, 0xb493f27e, v160
	v_fmaak_f32 v73, v72, v73, 0xbab60b61
	v_fmaak_f32 v73, v72, v73, 0x3d2aaaab
	v_fma_f32 v73, v72, v73, -0.5
	v_cndmask_b32_e32 v79, v86, v75, vcc
	v_fma_f32 v72, v72, v73, 1.0
	v_cmp_eq_u32_e32 vcc, 2, v71
	v_cmp_eq_u32_e64 s[8:9], 1, v71
	s_nop 0
	v_cndmask_b32_e64 v73, v70, -v72, vcc
	v_cndmask_b32_e32 v74, v72, v70, vcc
	v_cndmask_b32_e64 v73, v73, -v70, s[8:9]
	v_cndmask_b32_e64 v74, -v74, v72, s[8:9]
	v_cmp_eq_u32_e32 vcc, 0, v71
	v_mul_f32_e32 v71, v62, v66
	s_mov_b64 s[8:9], 0
	v_cndmask_b32_e32 v76, v73, v72, vcc
	v_cndmask_b32_e32 v77, v74, v70, vcc
	v_mul_f32_e32 v72, v54, v66
	v_mul_f32_e32 v74, v71, v80
	v_mul_f32_e32 v73, v72, v80
	v_fmac_f32_e32 v74, v72, v67
	v_mul_f32_e32 v72, v55, v66
	v_fma_f32 v73, v71, v67, -v73
	v_mul_f32_e32 v71, v63, v66
	v_mul_f32_e32 v75, v72, v81
	v_fma_f32 v75, v71, v78, -v75
	v_mul_f32_e32 v83, v71, v81
	v_mul_f32_e32 v71, v64, v66
	v_fmac_f32_e32 v83, v72, v78
	v_mul_f32_e32 v72, v56, v66
	v_mul_f32_e32 v85, v71, v82
	v_mul_f32_e32 v84, v72, v82
	v_fmac_f32_e32 v85, v72, v79
	v_mul_f32_e32 v72, v57, v66
	v_or_b32_e32 v70, s78, v68
	v_fma_f32 v84, v71, v79, -v84
	v_mul_f32_e32 v71, v65, v66
	v_mul_f32_e32 v86, v72, v77
	v_fma_f32 v86, v71, v76, -v86
	v_mul_f32_e32 v87, v71, v77
	v_mad_u64_u32 v[70:71], s[0:1], v70, s77, v[140:141]
	v_fmac_f32_e32 v87, v72, v76
	v_mad_i32_i24 v71, v69, s77, v71
	v_cvt_pk_bf16_f32 v72, v73, v75
	v_cvt_pk_bf16_f32 v73, v84, v86
	v_cvt_pk_bf16_f32 v74, v74, v83
	v_cvt_pk_bf16_f32 v75, v85, v87
	global_store_dwordx2 v[70:71], v[72:73], off offset:128
	global_store_dwordx2 v[70:71], v[74:75], off offset:160
	v_mul_f32_e32 v75, v50, v66
	v_mul_f32_e32 v74, v58, v66
	v_mul_f32_e32 v83, v75, v80
	v_fma_f32 v83, v74, v67, -v83
	v_mul_f32_e32 v80, v74, v80
	v_mul_f32_e32 v74, v51, v66
	v_fmac_f32_e32 v80, v75, v67
	v_mul_f32_e32 v67, v59, v66
	v_mul_f32_e32 v75, v74, v81
	v_fma_f32 v84, v67, v78, -v75
	v_mul_f32_e32 v67, v67, v81
	v_fmac_f32_e32 v67, v74, v78
	v_mul_f32_e32 v74, v60, v66
	v_mul_f32_e32 v75, v52, v66
	v_or_b32_e32 v72, s81, v68
	v_mov_b64_e32 v[70:71], s[24:25]
	v_mul_f32_e32 v78, v75, v82
	v_mul_f32_e32 v81, v74, v82
	v_mad_u64_u32 v[72:73], s[0:1], v72, s77, v[70:71]
	v_fma_f32 v78, v74, v79, -v78
	v_fmac_f32_e32 v81, v75, v79
	v_mul_f32_e32 v74, v61, v66
	v_mul_f32_e32 v75, v53, v66
	v_mad_i32_i24 v73, v69, s77, v73
	v_mul_f32_e32 v79, v75, v77
	v_mul_f32_e32 v82, v74, v77
	v_lshl_add_u64 v[70:71], v[72:73], 0, s[26:27]
	v_fma_f32 v79, v74, v76, -v79
	v_fmac_f32_e32 v82, v75, v76
	v_lshl_add_u64 v[74:75], v[72:73], 0, v[134:135]
	v_cvt_pk_bf16_f32 v76, v83, v84
	v_cvt_pk_bf16_f32 v77, v78, v79
	v_cvt_pk_bf16_f32 v72, v80, v67
	v_cvt_pk_bf16_f32 v73, v81, v82
	global_store_dwordx2 v[74:75], v[76:77], off offset:128

.LBB0_640:
	v_add_u32_e32 v58, 0x90, v146
	v_lshl_add_u64 v[50:51], v[70:71], 0, v[134:135]
	v_ashrrev_i32_e32 v59, 31, v58
	global_store_dwordx2 v[50:51], v[72:73], off offset:32
	v_lshlrev_b64 v[50:51], 5, v[58:59]
	v_lshl_add_u64 v[50:51], s[10:11], 0, v[50:51]
	v_mov_b32_e32 v50, v198
	v_mov_b32_e32 v51, v199
	v_mov_b32_e32 v52, v200
	v_mov_b32_e32 v53, v201
	s_and_b64 vcc, exec, s[6:7]
	s_mov_b64 s[8:9], -1
	v_add_f32_e32 v50, v50, v51
	v_add_f32_e32 v51, v52, v53
	v_add_f32_e32 v50, v50, v51
	v_fmamk_f32 v50, v50, 0x3b800000, v158
	v_rsq_f32_e32 v50, v50
	v_lshlrev_b64 v[52:53], 3, v[58:59]
	v_mul_f32_e32 v50, 0x3e16c740, v50
	s_cbranch_vccnz .LBB0_642
	v_mov_b32_e32 v54, v210
	v_mov_b32_e32 v55, v211
	v_mov_b32_e32 v56, v212
	v_mov_b32_e32 v57, v213
	v_and_b32_e32 v51, 0x1fdf, v58
	v_cvt_f32_u32_e32 v51, v51
	v_mul_f32_e32 v54, v54, v51
	v_mul_f32_e32 v58, v55, v51
	v_cvt_f64_f32_e32 v[54:55], v54
	v_mul_f32_e32 v59, v56, v51
	v_mul_f32_e32 v51, v57, v51
	v_cvt_f64_f32_e32 v[56:57], v58
	v_mul_f64 v[62:63], v[54:55], s[42:43]
	v_cvt_f64_f32_e32 v[58:59], v59
	v_mul_f64 v[64:65], v[56:57], s[42:43]
	v_rndne_f64_e32 v[62:63], v[62:63]
	v_mul_f64 v[66:67], v[58:59], s[42:43]
	v_rndne_f64_e32 v[64:65], v[64:65]
	v_fma_f64 v[54:55], v[54:55], s[42:43], -v[62:63]
	v_rndne_f64_e32 v[66:67], v[66:67]
	v_fma_f64 v[56:57], v[56:57], s[42:43], -v[64:65]
	v_mul_f64 v[54:55], v[54:55], s[44:45]
	v_fma_f64 v[58:59], v[58:59], s[42:43], -v[66:67]
	v_mul_f64 v[56:57], v[56:57], s[44:45]
	v_cvt_f32_f64_e32 v54, v[54:55]
	v_mul_f64 v[58:59], v[58:59], s[44:45]
	v_cvt_f32_f64_e32 v55, v[56:57]
	v_mul_f32_e32 v57, v54, v54
	v_cvt_f64_f32_e32 v[60:61], v51
	v_cvt_i32_f64_e32 v51, v[62:63]
	v_cvt_i32_f64_e32 v62, v[64:65]
	v_cvt_f32_f64_e32 v56, v[58:59]
	v_mul_f32_e32 v58, v55, v55
	v_fmamk_f32 v64, v57, 0x3638ef1d, v159
	v_fmamk_f32 v65, v57, 0xb493f27e, v160
	v_cvt_i32_f64_e32 v63, v[66:67]
	v_mul_f32_e32 v59, v56, v56
	v_fmamk_f32 v66, v58, 0x3638ef1d, v159
	v_fmamk_f32 v67, v58, 0xb493f27e, v160
	v_fmaak_f32 v64, v57, v64, 0x3c088888
	v_fmaak_f32 v65, v57, v65, 0xbab60b61
	v_fmamk_f32 v70, v59, 0x3638ef1d, v159
	v_fmamk_f32 v71, v59, 0xb493f27e, v160
	v_fmaak_f32 v66, v58, v66, 0x3c088888
	v_fmaak_f32 v67, v58, v67, 0xbab60b61
	v_fmaak_f32 v64, v57, v64, 0xbe2aaaab
	v_fmaak_f32 v65, v57, v65, 0x3d2aaaab
	v_and_b32_e32 v51, 3, v51
	v_fmaak_f32 v70, v59, v70, 0x3c088888
	v_fmaak_f32 v71, v59, v71, 0xbab60b61
	v_fmaak_f32 v66, v58, v66, 0xbe2aaaab
	v_fmaak_f32 v67, v58, v67, 0x3d2aaaab
	v_fma_f32 v64, v57, v64, 1.0
	v_fma_f32 v65, v57, v65, -0.5
	v_and_b32_e32 v62, 3, v62
	v_fmaak_f32 v70, v59, v70, 0xbe2aaaab
	v_fmaak_f32 v71, v59, v71, 0x3d2aaaab
	v_fma_f32 v66, v58, v66, 1.0
	v_fma_f32 v67, v58, v67, -0.5
	v_mul_f32_e32 v54, v64, v54
	v_fma_f32 v57, v57, v65, 1.0
	v_cmp_eq_u32_e32 vcc, 2, v51
	v_and_b32_e32 v63, 3, v63
	v_fma_f32 v70, v59, v70, 1.0
	v_fma_f32 v71, v59, v71, -0.5
	v_mul_f32_e32 v55, v66, v55
	v_fma_f32 v58, v58, v67, 1.0
	v_cndmask_b32_e64 v64, v54, -v57, vcc
	v_cndmask_b32_e32 v65, v57, v54, vcc
	v_cmp_eq_u32_e32 vcc, 2, v62
	v_mul_f32_e32 v56, v70, v56
	v_fma_f32 v59, v59, v71, 1.0
	v_cndmask_b32_e64 v66, v55, -v58, vcc
	v_cndmask_b32_e32 v67, v58, v55, vcc
	v_cmp_eq_u32_e32 vcc, 2, v63
	v_mul_f64 v[68:69], v[60:61], s[42:43]
	v_rndne_f64_e32 v[68:69], v[68:69]
	v_cndmask_b32_e64 v70, v56, -v59, vcc
	v_cndmask_b32_e32 v71, v59, v56, vcc
	v_cmp_eq_u32_e32 vcc, 1, v51
	v_fma_f64 v[60:61], v[60:61], s[42:43], -v[68:69]
	v_mul_f64 v[60:61], v[60:61], s[44:45]
	v_cndmask_b32_e64 v64, v64, -v54, vcc
	v_cndmask_b32_e64 v65, -v65, v57, vcc
	v_cmp_eq_u32_e32 vcc, 1, v62
	s_nop 1
	v_cndmask_b32_e64 v66, v66, -v55, vcc
	v_cndmask_b32_e64 v67, -v67, v58, vcc
	v_cmp_eq_u32_e32 vcc, 1, v63
	s_nop 1
	v_cndmask_b32_e64 v70, v70, -v56, vcc
	v_cndmask_b32_e64 v71, -v71, v59, vcc
	v_cmp_eq_u32_e32 vcc, 0, v51
	s_nop 1
	v_cndmask_b32_e32 v51, v64, v57, vcc
	v_cndmask_b32_e32 v64, v65, v54, vcc
	v_cmp_eq_u32_e32 vcc, 0, v62
	v_cvt_f32_f64_e32 v54, v[60:61]
	s_nop 0
	v_cndmask_b32_e32 v62, v66, v58, vcc
	v_cndmask_b32_e32 v65, v67, v55, vcc
	v_cmp_eq_u32_e32 vcc, 0, v63
	v_cvt_i32_f64_e32 v55, v[68:69]
	v_and_b32_e32 v55, 3, v55
	v_cndmask_b32_e32 v66, v71, v56, vcc
	v_mul_f32_e32 v56, v54, v54
	v_fmamk_f32 v57, v56, 0x3638ef1d, v159
	v_fmaak_f32 v57, v56, v57, 0x3c088888
	v_fmaak_f32 v57, v56, v57, 0xbe2aaaab
	v_fma_f32 v57, v56, v57, 1.0
	v_mul_f32_e32 v54, v57, v54
	v_fmamk_f32 v57, v56, 0xb493f27e, v160
	v_fmaak_f32 v57, v56, v57, 0xbab60b61
	v_fmaak_f32 v57, v56, v57, 0x3d2aaaab
	v_fma_f32 v57, v56, v57, -0.5
	v_cndmask_b32_e32 v63, v70, v59, vcc
	v_fma_f32 v56, v56, v57, 1.0
	v_cmp_eq_u32_e32 vcc, 2, v55
	v_cmp_eq_u32_e64 s[8:9], 1, v55
	s_nop 0
	v_cndmask_b32_e64 v57, v54, -v56, vcc
	v_cndmask_b32_e32 v58, v56, v54, vcc
	v_cndmask_b32_e64 v57, v57, -v54, s[8:9]
	v_cndmask_b32_e64 v58, -v58, v56, s[8:9]
	v_cmp_eq_u32_e32 vcc, 0, v55
	v_mul_f32_e32 v55, v46, v50
	s_mov_b64 s[8:9], 0
	v_cndmask_b32_e32 v60, v57, v56, vcc
	v_cndmask_b32_e32 v61, v58, v54, vcc
	v_mul_f32_e32 v56, v38, v50
	v_mul_f32_e32 v58, v55, v64
	v_mul_f32_e32 v57, v56, v64
	v_fmac_f32_e32 v58, v56, v51
	v_mul_f32_e32 v56, v39, v50
	v_fma_f32 v57, v55, v51, -v57
	v_mul_f32_e32 v55, v47, v50
	v_mul_f32_e32 v59, v56, v65
	v_fma_f32 v59, v55, v62, -v59
	v_mul_f32_e32 v67, v55, v65
	v_mul_f32_e32 v55, v48, v50
	v_fmac_f32_e32 v67, v56, v62
	v_mul_f32_e32 v56, v40, v50
	v_mul_f32_e32 v69, v55, v66
	v_mul_f32_e32 v68, v56, v66
	v_fmac_f32_e32 v69, v56, v63
	v_mul_f32_e32 v56, v41, v50
	v_or_b32_e32 v54, s78, v52
	v_fma_f32 v68, v55, v63, -v68
	v_mul_f32_e32 v55, v49, v50
	v_mul_f32_e32 v70, v56, v61
	v_fma_f32 v70, v55, v60, -v70
	v_mul_f32_e32 v71, v55, v61
	v_mad_u64_u32 v[54:55], s[0:1], v54, s77, v[140:141]
	v_fmac_f32_e32 v71, v56, v60
	v_mad_i32_i24 v55, v53, s77, v55
	v_cvt_pk_bf16_f32 v56, v57, v59
	v_cvt_pk_bf16_f32 v57, v68, v70
	v_cvt_pk_bf16_f32 v58, v58, v67
	v_cvt_pk_bf16_f32 v59, v69, v71
	global_store_dwordx2 v[54:55], v[56:57], off offset:128
	global_store_dwordx2 v[54:55], v[58:59], off offset:160
	v_mul_f32_e32 v59, v34, v50
	v_mul_f32_e32 v58, v42, v50
	v_mul_f32_e32 v67, v59, v64
	v_fma_f32 v67, v58, v51, -v67
	v_mul_f32_e32 v64, v58, v64
	v_mul_f32_e32 v58, v35, v50
	v_fmac_f32_e32 v64, v59, v51
	v_mul_f32_e32 v51, v43, v50
	v_mul_f32_e32 v59, v58, v65
	v_fma_f32 v68, v51, v62, -v59
	v_mul_f32_e32 v51, v51, v65
	v_fmac_f32_e32 v51, v58, v62
	v_mul_f32_e32 v58, v44, v50
	v_mul_f32_e32 v59, v36, v50
	v_or_b32_e32 v56, s81, v52
	v_mov_b64_e32 v[54:55], s[24:25]
	v_mul_f32_e32 v62, v59, v66
	v_mul_f32_e32 v65, v58, v66
	v_mad_u64_u32 v[56:57], s[0:1], v56, s77, v[54:55]
	v_fma_f32 v62, v58, v63, -v62
	v_fmac_f32_e32 v65, v59, v63
	v_mul_f32_e32 v58, v45, v50
	v_mul_f32_e32 v59, v37, v50
	v_mad_i32_i24 v57, v53, s77, v57
	v_mul_f32_e32 v63, v59, v61
	v_mul_f32_e32 v66, v58, v61
	v_lshl_add_u64 v[54:55], v[56:57], 0, s[26:27]
	v_fma_f32 v63, v58, v60, -v63
	v_fmac_f32_e32 v66, v59, v60
	v_lshl_add_u64 v[58:59], v[56:57], 0, v[134:135]
	v_cvt_pk_bf16_f32 v60, v67, v68
	v_cvt_pk_bf16_f32 v61, v62, v63
	v_cvt_pk_bf16_f32 v56, v64, v51
	v_cvt_pk_bf16_f32 v57, v65, v66
	global_store_dwordx2 v[58:59], v[60:61], off offset:128

.LBB0_644:
	v_add_u32_e32 v42, 0xa0, v146
	v_lshl_add_u64 v[34:35], v[54:55], 0, v[134:135]
	v_ashrrev_i32_e32 v43, 31, v42
	global_store_dwordx2 v[34:35], v[56:57], off offset:32
	v_lshlrev_b64 v[34:35], 5, v[42:43]
	v_lshl_add_u64 v[34:35], s[10:11], 0, v[34:35]
	v_mov_b32_e32 v34, v202
	v_mov_b32_e32 v35, v203
	v_mov_b32_e32 v36, v204
	v_mov_b32_e32 v37, v205
	s_and_b64 vcc, exec, s[6:7]
	s_mov_b64 s[8:9], -1
	v_add_f32_e32 v34, v34, v35
	v_add_f32_e32 v35, v36, v37
	v_add_f32_e32 v34, v34, v35
	v_fmamk_f32 v34, v34, 0x3b800000, v158
	v_rsq_f32_e32 v34, v34
	v_lshlrev_b64 v[36:37], 3, v[42:43]
	v_mul_f32_e32 v34, 0x3e16c740, v34
	s_cbranch_vccnz .LBB0_646
	v_mov_b32_e32 v38, v210
	v_mov_b32_e32 v39, v211
	v_mov_b32_e32 v40, v212
	v_mov_b32_e32 v41, v213
	v_and_b32_e32 v35, 0x1fef, v42
	v_cvt_f32_u32_e32 v35, v35
	v_mul_f32_e32 v38, v38, v35
	v_mul_f32_e32 v42, v39, v35
	v_cvt_f64_f32_e32 v[38:39], v38
	v_mul_f32_e32 v43, v40, v35
	v_mul_f32_e32 v35, v41, v35
	v_cvt_f64_f32_e32 v[40:41], v42
	v_mul_f64 v[46:47], v[38:39], s[42:43]
	v_cvt_f64_f32_e32 v[42:43], v43
	v_mul_f64 v[48:49], v[40:41], s[42:43]
	v_rndne_f64_e32 v[46:47], v[46:47]
	v_mul_f64 v[50:51], v[42:43], s[42:43]
	v_rndne_f64_e32 v[48:49], v[48:49]
	v_fma_f64 v[38:39], v[38:39], s[42:43], -v[46:47]
	v_rndne_f64_e32 v[50:51], v[50:51]
	v_fma_f64 v[40:41], v[40:41], s[42:43], -v[48:49]
	v_mul_f64 v[38:39], v[38:39], s[44:45]
	v_fma_f64 v[42:43], v[42:43], s[42:43], -v[50:51]
	v_mul_f64 v[40:41], v[40:41], s[44:45]
	v_cvt_f32_f64_e32 v38, v[38:39]
	v_mul_f64 v[42:43], v[42:43], s[44:45]
	v_cvt_f32_f64_e32 v39, v[40:41]
	v_mul_f32_e32 v41, v38, v38
	v_cvt_f64_f32_e32 v[44:45], v35
	v_cvt_i32_f64_e32 v35, v[46:47]
	v_cvt_i32_f64_e32 v46, v[48:49]
	v_cvt_f32_f64_e32 v40, v[42:43]
	v_mul_f32_e32 v42, v39, v39
	v_fmamk_f32 v48, v41, 0x3638ef1d, v159
	v_fmamk_f32 v49, v41, 0xb493f27e, v160
	v_cvt_i32_f64_e32 v47, v[50:51]
	v_mul_f32_e32 v43, v40, v40
	v_fmamk_f32 v50, v42, 0x3638ef1d, v159
	v_fmamk_f32 v51, v42, 0xb493f27e, v160
	v_fmaak_f32 v48, v41, v48, 0x3c088888
	v_fmaak_f32 v49, v41, v49, 0xbab60b61
	v_fmamk_f32 v54, v43, 0x3638ef1d, v159
	v_fmamk_f32 v55, v43, 0xb493f27e, v160
	v_fmaak_f32 v50, v42, v50, 0x3c088888
	v_fmaak_f32 v51, v42, v51, 0xbab60b61
	v_fmaak_f32 v48, v41, v48, 0xbe2aaaab
	v_fmaak_f32 v49, v41, v49, 0x3d2aaaab
	v_and_b32_e32 v35, 3, v35
	v_fmaak_f32 v54, v43, v54, 0x3c088888
	v_fmaak_f32 v55, v43, v55, 0xbab60b61
	v_fmaak_f32 v50, v42, v50, 0xbe2aaaab
	v_fmaak_f32 v51, v42, v51, 0x3d2aaaab
	v_fma_f32 v48, v41, v48, 1.0
	v_fma_f32 v49, v41, v49, -0.5
	v_and_b32_e32 v46, 3, v46
	v_fmaak_f32 v54, v43, v54, 0xbe2aaaab
	v_fmaak_f32 v55, v43, v55, 0x3d2aaaab
	v_fma_f32 v50, v42, v50, 1.0
	v_fma_f32 v51, v42, v51, -0.5
	v_mul_f32_e32 v38, v48, v38
	v_fma_f32 v41, v41, v49, 1.0
	v_cmp_eq_u32_e32 vcc, 2, v35
	v_and_b32_e32 v47, 3, v47
	v_fma_f32 v54, v43, v54, 1.0
	v_fma_f32 v55, v43, v55, -0.5
	v_mul_f32_e32 v39, v50, v39
	v_fma_f32 v42, v42, v51, 1.0
	v_cndmask_b32_e64 v48, v38, -v41, vcc
	v_cndmask_b32_e32 v49, v41, v38, vcc
	v_cmp_eq_u32_e32 vcc, 2, v46
	v_mul_f32_e32 v40, v54, v40
	v_fma_f32 v43, v43, v55, 1.0
	v_cndmask_b32_e64 v50, v39, -v42, vcc
	v_cndmask_b32_e32 v51, v42, v39, vcc
	v_cmp_eq_u32_e32 vcc, 2, v47
	v_mul_f64 v[52:53], v[44:45], s[42:43]
	v_rndne_f64_e32 v[52:53], v[52:53]
	v_cndmask_b32_e64 v54, v40, -v43, vcc
	v_cndmask_b32_e32 v55, v43, v40, vcc
	v_cmp_eq_u32_e32 vcc, 1, v35
	v_fma_f64 v[44:45], v[44:45], s[42:43], -v[52:53]
	v_mul_f64 v[44:45], v[44:45], s[44:45]
	v_cndmask_b32_e64 v48, v48, -v38, vcc
	v_cndmask_b32_e64 v49, -v49, v41, vcc
	v_cmp_eq_u32_e32 vcc, 1, v46
	s_nop 1
	v_cndmask_b32_e64 v50, v50, -v39, vcc
	v_cndmask_b32_e64 v51, -v51, v42, vcc
	v_cmp_eq_u32_e32 vcc, 1, v47
	s_nop 1
	v_cndmask_b32_e64 v54, v54, -v40, vcc
	v_cndmask_b32_e64 v55, -v55, v43, vcc
	v_cmp_eq_u32_e32 vcc, 0, v35
	s_nop 1
	v_cndmask_b32_e32 v35, v48, v41, vcc
	v_cndmask_b32_e32 v48, v49, v38, vcc
	v_cmp_eq_u32_e32 vcc, 0, v46
	v_cvt_f32_f64_e32 v38, v[44:45]
	s_nop 0
	v_cndmask_b32_e32 v46, v50, v42, vcc
	v_cndmask_b32_e32 v49, v51, v39, vcc
	v_cmp_eq_u32_e32 vcc, 0, v47
	v_cvt_i32_f64_e32 v39, v[52:53]
	v_and_b32_e32 v39, 3, v39
	v_cndmask_b32_e32 v50, v55, v40, vcc
	v_mul_f32_e32 v40, v38, v38
	v_fmamk_f32 v41, v40, 0x3638ef1d, v159
	v_fmaak_f32 v41, v40, v41, 0x3c088888
	v_fmaak_f32 v41, v40, v41, 0xbe2aaaab
	v_fma_f32 v41, v40, v41, 1.0
	v_mul_f32_e32 v38, v41, v38
	v_fmamk_f32 v41, v40, 0xb493f27e, v160
	v_fmaak_f32 v41, v40, v41, 0xbab60b61
	v_fmaak_f32 v41, v40, v41, 0x3d2aaaab
	v_fma_f32 v41, v40, v41, -0.5
	v_cndmask_b32_e32 v47, v54, v43, vcc
	v_fma_f32 v40, v40, v41, 1.0
	v_cmp_eq_u32_e32 vcc, 2, v39
	v_cmp_eq_u32_e64 s[8:9], 1, v39
	s_nop 0
	v_cndmask_b32_e64 v41, v38, -v40, vcc
	v_cndmask_b32_e32 v42, v40, v38, vcc
	v_cndmask_b32_e64 v41, v41, -v38, s[8:9]
	v_cndmask_b32_e64 v42, -v42, v40, s[8:9]
	v_cmp_eq_u32_e32 vcc, 0, v39
	v_mul_f32_e32 v39, v30, v34
	s_mov_b64 s[8:9], 0
	v_cndmask_b32_e32 v44, v41, v40, vcc
	v_cndmask_b32_e32 v45, v42, v38, vcc
	v_mul_f32_e32 v40, v22, v34
	v_mul_f32_e32 v42, v39, v48
	v_mul_f32_e32 v41, v40, v48
	v_fmac_f32_e32 v42, v40, v35
	v_mul_f32_e32 v40, v23, v34
	v_fma_f32 v41, v39, v35, -v41
	v_mul_f32_e32 v39, v31, v34
	v_mul_f32_e32 v43, v40, v49
	v_fma_f32 v43, v39, v46, -v43
	v_mul_f32_e32 v51, v39, v49
	v_mul_f32_e32 v39, v32, v34
	v_fmac_f32_e32 v51, v40, v46
	v_mul_f32_e32 v40, v24, v34
	v_mul_f32_e32 v53, v39, v50
	v_mul_f32_e32 v52, v40, v50
	v_fmac_f32_e32 v53, v40, v47
	v_mul_f32_e32 v40, v25, v34
	v_or_b32_e32 v38, s78, v36
	v_fma_f32 v52, v39, v47, -v52
	v_mul_f32_e32 v39, v33, v34
	v_mul_f32_e32 v54, v40, v45
	v_fma_f32 v54, v39, v44, -v54
	v_mul_f32_e32 v55, v39, v45
	v_mad_u64_u32 v[38:39], s[0:1], v38, s77, v[140:141]
	v_fmac_f32_e32 v55, v40, v44
	v_mad_i32_i24 v39, v37, s77, v39
	v_cvt_pk_bf16_f32 v40, v41, v43
	v_cvt_pk_bf16_f32 v41, v52, v54
	v_cvt_pk_bf16_f32 v42, v42, v51
	v_cvt_pk_bf16_f32 v43, v53, v55
	global_store_dwordx2 v[38:39], v[40:41], off offset:128
	global_store_dwordx2 v[38:39], v[42:43], off offset:160
	v_mul_f32_e32 v43, v18, v34
	v_mul_f32_e32 v42, v26, v34
	v_mul_f32_e32 v51, v43, v48
	v_fma_f32 v51, v42, v35, -v51
	v_mul_f32_e32 v48, v42, v48
	v_mul_f32_e32 v42, v19, v34
	v_fmac_f32_e32 v48, v43, v35
	v_mul_f32_e32 v35, v27, v34
	v_mul_f32_e32 v43, v42, v49
	v_fma_f32 v52, v35, v46, -v43
	v_mul_f32_e32 v35, v35, v49
	v_fmac_f32_e32 v35, v42, v46
	v_mul_f32_e32 v42, v28, v34
	v_mul_f32_e32 v43, v20, v34
	v_or_b32_e32 v40, s81, v36
	v_mov_b64_e32 v[38:39], s[24:25]
	v_mul_f32_e32 v46, v43, v50
	v_mul_f32_e32 v49, v42, v50
	v_mad_u64_u32 v[40:41], s[0:1], v40, s77, v[38:39]
	v_fma_f32 v46, v42, v47, -v46
	v_fmac_f32_e32 v49, v43, v47
	v_mul_f32_e32 v42, v29, v34
	v_mul_f32_e32 v43, v21, v34
	v_mad_i32_i24 v41, v37, s77, v41
	v_mul_f32_e32 v47, v43, v45
	v_mul_f32_e32 v50, v42, v45
	v_lshl_add_u64 v[38:39], v[40:41], 0, s[26:27]
	v_fma_f32 v47, v42, v44, -v47
	v_fmac_f32_e32 v50, v43, v44
	v_lshl_add_u64 v[42:43], v[40:41], 0, v[134:135]
	v_cvt_pk_bf16_f32 v44, v51, v52
	v_cvt_pk_bf16_f32 v45, v46, v47
	v_cvt_pk_bf16_f32 v40, v48, v35
	v_cvt_pk_bf16_f32 v41, v49, v50
	global_store_dwordx2 v[42:43], v[44:45], off offset:128

.LBB0_648:
	v_add_u32_e32 v26, 0xb0, v146
	v_lshl_add_u64 v[18:19], v[38:39], 0, v[134:135]
	v_ashrrev_i32_e32 v27, 31, v26
	global_store_dwordx2 v[18:19], v[40:41], off offset:32
	v_lshlrev_b64 v[18:19], 5, v[26:27]
	v_lshl_add_u64 v[18:19], s[10:11], 0, v[18:19]
	v_mov_b32_e32 v18, v206
	v_mov_b32_e32 v19, v207
	v_mov_b32_e32 v20, v208
	v_mov_b32_e32 v21, v209
	s_and_b64 vcc, exec, s[6:7]
	s_mov_b64 s[6:7], -1
	v_add_f32_e32 v18, v18, v19
	v_add_f32_e32 v19, v20, v21
	v_add_f32_e32 v18, v18, v19
	v_fmamk_f32 v18, v18, 0x3b800000, v158
	v_rsq_f32_e32 v18, v18
	v_lshlrev_b64 v[20:21], 3, v[26:27]
	v_mul_f32_e32 v18, 0x3e16c740, v18
	s_cbranch_vccnz .LBB0_650
	v_mov_b32_e32 v22, v210
	v_mov_b32_e32 v23, v211
	v_mov_b32_e32 v24, v212
	v_mov_b32_e32 v25, v213
	v_and_b32_e32 v19, 0x1fff, v26
	v_cvt_f32_u32_e32 v19, v19
	v_mul_f32_e32 v22, v22, v19
	v_mul_f32_e32 v26, v23, v19
	v_cvt_f64_f32_e32 v[22:23], v22
	v_mul_f32_e32 v27, v24, v19
	v_mul_f32_e32 v19, v25, v19
	v_cvt_f64_f32_e32 v[24:25], v26
	v_mul_f64 v[30:31], v[22:23], s[42:43]
	v_cvt_f64_f32_e32 v[26:27], v27
	v_mul_f64 v[32:33], v[24:25], s[42:43]
	v_rndne_f64_e32 v[30:31], v[30:31]
	v_mul_f64 v[34:35], v[26:27], s[42:43]
	v_rndne_f64_e32 v[32:33], v[32:33]
	v_fma_f64 v[22:23], v[22:23], s[42:43], -v[30:31]
	v_rndne_f64_e32 v[34:35], v[34:35]
	v_fma_f64 v[24:25], v[24:25], s[42:43], -v[32:33]
	v_mul_f64 v[22:23], v[22:23], s[44:45]
	v_fma_f64 v[26:27], v[26:27], s[42:43], -v[34:35]
	v_mul_f64 v[24:25], v[24:25], s[44:45]
	v_cvt_f32_f64_e32 v22, v[22:23]
	v_mul_f64 v[26:27], v[26:27], s[44:45]
	v_cvt_f32_f64_e32 v23, v[24:25]
	v_mul_f32_e32 v25, v22, v22
	v_cvt_f64_f32_e32 v[28:29], v19
	v_cvt_i32_f64_e32 v19, v[30:31]
	v_cvt_i32_f64_e32 v30, v[32:33]
	v_cvt_f32_f64_e32 v24, v[26:27]
	v_mul_f32_e32 v26, v23, v23
	v_fmamk_f32 v32, v25, 0x3638ef1d, v159
	v_fmamk_f32 v33, v25, 0xb493f27e, v160
	v_cvt_i32_f64_e32 v31, v[34:35]
	v_mul_f32_e32 v27, v24, v24
	v_fmamk_f32 v34, v26, 0x3638ef1d, v159
	v_fmamk_f32 v35, v26, 0xb493f27e, v160
	v_fmaak_f32 v32, v25, v32, 0x3c088888
	v_fmaak_f32 v33, v25, v33, 0xbab60b61
	v_fmamk_f32 v38, v27, 0x3638ef1d, v159
	v_fmamk_f32 v39, v27, 0xb493f27e, v160
	v_fmaak_f32 v34, v26, v34, 0x3c088888
	v_fmaak_f32 v35, v26, v35, 0xbab60b61
	v_fmaak_f32 v32, v25, v32, 0xbe2aaaab
	v_fmaak_f32 v33, v25, v33, 0x3d2aaaab
	v_and_b32_e32 v19, 3, v19
	v_fmaak_f32 v38, v27, v38, 0x3c088888
	v_fmaak_f32 v39, v27, v39, 0xbab60b61
	v_fmaak_f32 v34, v26, v34, 0xbe2aaaab
	v_fmaak_f32 v35, v26, v35, 0x3d2aaaab
	v_fma_f32 v32, v25, v32, 1.0
	v_fma_f32 v33, v25, v33, -0.5
	v_and_b32_e32 v30, 3, v30
	v_fmaak_f32 v38, v27, v38, 0xbe2aaaab
	v_fmaak_f32 v39, v27, v39, 0x3d2aaaab
	v_fma_f32 v34, v26, v34, 1.0
	v_fma_f32 v35, v26, v35, -0.5
	v_mul_f32_e32 v22, v32, v22
	v_fma_f32 v25, v25, v33, 1.0
	v_cmp_eq_u32_e32 vcc, 2, v19
	v_and_b32_e32 v31, 3, v31
	v_fma_f32 v38, v27, v38, 1.0
	v_fma_f32 v39, v27, v39, -0.5
	v_mul_f32_e32 v23, v34, v23
	v_fma_f32 v26, v26, v35, 1.0
	v_cndmask_b32_e64 v32, v22, -v25, vcc
	v_cndmask_b32_e32 v33, v25, v22, vcc
	v_cmp_eq_u32_e32 vcc, 2, v30
	v_mul_f32_e32 v24, v38, v24
	v_fma_f32 v27, v27, v39, 1.0
	v_cndmask_b32_e64 v34, v23, -v26, vcc
	v_cndmask_b32_e32 v35, v26, v23, vcc
	v_cmp_eq_u32_e32 vcc, 2, v31
	v_mul_f64 v[36:37], v[28:29], s[42:43]
	v_rndne_f64_e32 v[36:37], v[36:37]
	v_cndmask_b32_e64 v38, v24, -v27, vcc
	v_cndmask_b32_e32 v39, v27, v24, vcc
	v_cmp_eq_u32_e32 vcc, 1, v19
	v_fma_f64 v[28:29], v[28:29], s[42:43], -v[36:37]
	v_mul_f64 v[28:29], v[28:29], s[44:45]
	v_cndmask_b32_e64 v32, v32, -v22, vcc
	v_cndmask_b32_e64 v33, -v33, v25, vcc
	v_cmp_eq_u32_e32 vcc, 1, v30
	s_nop 1
	v_cndmask_b32_e64 v34, v34, -v23, vcc
	v_cndmask_b32_e64 v35, -v35, v26, vcc
	v_cmp_eq_u32_e32 vcc, 1, v31
	s_nop 1
	v_cndmask_b32_e64 v38, v38, -v24, vcc
	v_cndmask_b32_e64 v39, -v39, v27, vcc
	v_cmp_eq_u32_e32 vcc, 0, v19
	s_nop 1
	v_cndmask_b32_e32 v19, v32, v25, vcc
	v_cndmask_b32_e32 v32, v33, v22, vcc
	v_cmp_eq_u32_e32 vcc, 0, v30
	v_cvt_f32_f64_e32 v22, v[28:29]
	s_nop 0
	v_cndmask_b32_e32 v30, v34, v26, vcc
	v_cndmask_b32_e32 v33, v35, v23, vcc
	v_cmp_eq_u32_e32 vcc, 0, v31
	v_cvt_i32_f64_e32 v23, v[36:37]
	v_and_b32_e32 v23, 3, v23
	v_cndmask_b32_e32 v34, v39, v24, vcc
	v_mul_f32_e32 v24, v22, v22
	v_fmamk_f32 v25, v24, 0x3638ef1d, v159
	v_fmaak_f32 v25, v24, v25, 0x3c088888
	v_fmaak_f32 v25, v24, v25, 0xbe2aaaab
	v_fma_f32 v25, v24, v25, 1.0
	v_mul_f32_e32 v22, v25, v22
	v_fmamk_f32 v25, v24, 0xb493f27e, v160
	v_fmaak_f32 v25, v24, v25, 0xbab60b61
	v_fmaak_f32 v25, v24, v25, 0x3d2aaaab
	v_fma_f32 v25, v24, v25, -0.5
	v_cndmask_b32_e32 v31, v38, v27, vcc
	v_fma_f32 v24, v24, v25, 1.0
	v_cmp_eq_u32_e32 vcc, 2, v23
	v_cmp_eq_u32_e64 s[6:7], 1, v23
	s_nop 0
	v_cndmask_b32_e64 v25, v22, -v24, vcc
	v_cndmask_b32_e32 v26, v24, v22, vcc
	v_cndmask_b32_e64 v25, v25, -v22, s[6:7]
	v_cndmask_b32_e64 v26, -v26, v24, s[6:7]
	v_cmp_eq_u32_e32 vcc, 0, v23
	v_mul_f32_e32 v23, v14, v18
	s_mov_b64 s[6:7], 0
	v_cndmask_b32_e32 v28, v25, v24, vcc
	v_cndmask_b32_e32 v29, v26, v22, vcc
	v_mul_f32_e32 v24, v6, v18
	v_mul_f32_e32 v26, v23, v32
	v_mul_f32_e32 v25, v24, v32
	v_fmac_f32_e32 v26, v24, v19
	v_mul_f32_e32 v24, v7, v18
	v_fma_f32 v25, v23, v19, -v25
	v_mul_f32_e32 v23, v15, v18
	v_mul_f32_e32 v27, v24, v33
	v_fma_f32 v27, v23, v30, -v27
	v_mul_f32_e32 v35, v23, v33
	v_mul_f32_e32 v23, v16, v18
	v_fmac_f32_e32 v35, v24, v30
	v_mul_f32_e32 v24, v8, v18
	v_mul_f32_e32 v37, v23, v34
	v_mul_f32_e32 v36, v24, v34
	v_fmac_f32_e32 v37, v24, v31
	v_mul_f32_e32 v24, v9, v18
	v_or_b32_e32 v22, s78, v20
	v_fma_f32 v36, v23, v31, -v36
	v_mul_f32_e32 v23, v17, v18
	v_mul_f32_e32 v38, v24, v29
	v_fma_f32 v38, v23, v28, -v38
	v_mul_f32_e32 v39, v23, v29
	v_mad_u64_u32 v[22:23], s[0:1], v22, s77, v[140:141]
	v_fmac_f32_e32 v39, v24, v28
	v_mad_i32_i24 v23, v21, s77, v23
	v_cvt_pk_bf16_f32 v24, v25, v27
	v_cvt_pk_bf16_f32 v25, v36, v38
	v_cvt_pk_bf16_f32 v26, v26, v35
	v_cvt_pk_bf16_f32 v27, v37, v39
	global_store_dwordx2 v[22:23], v[24:25], off offset:128
	global_store_dwordx2 v[22:23], v[26:27], off offset:160
	v_mul_f32_e32 v27, v2, v18
	v_mul_f32_e32 v26, v10, v18
	v_mul_f32_e32 v35, v27, v32
	v_fma_f32 v35, v26, v19, -v35
	v_mul_f32_e32 v32, v26, v32
	v_mul_f32_e32 v26, v3, v18
	v_fmac_f32_e32 v32, v27, v19
	v_mul_f32_e32 v19, v11, v18
	v_mul_f32_e32 v27, v26, v33
	v_fma_f32 v36, v19, v30, -v27
	v_mul_f32_e32 v19, v19, v33
	v_fmac_f32_e32 v19, v26, v30
	v_mul_f32_e32 v26, v12, v18
	v_mul_f32_e32 v27, v4, v18
	v_or_b32_e32 v24, s81, v20
	v_mov_b64_e32 v[22:23], s[24:25]
	v_mul_f32_e32 v30, v27, v34
	v_mul_f32_e32 v33, v26, v34
	v_mad_u64_u32 v[24:25], s[0:1], v24, s77, v[22:23]
	v_fma_f32 v30, v26, v31, -v30
	v_fmac_f32_e32 v33, v27, v31
	v_mul_f32_e32 v26, v13, v18
	v_mul_f32_e32 v27, v5, v18
	v_mad_i32_i24 v25, v21, s77, v25
	v_mul_f32_e32 v31, v27, v29
	v_mul_f32_e32 v34, v26, v29
	v_lshl_add_u64 v[22:23], v[24:25], 0, s[26:27]
	v_fma_f32 v31, v26, v28, -v31
	v_fmac_f32_e32 v34, v27, v28
	v_lshl_add_u64 v[26:27], v[24:25], 0, v[134:135]
	v_cvt_pk_bf16_f32 v28, v35, v36
	v_cvt_pk_bf16_f32 v29, v30, v31
	v_cvt_pk_bf16_f32 v24, v32, v19
	v_cvt_pk_bf16_f32 v25, v33, v34
	global_store_dwordx2 v[26:27], v[28:29], off offset:128
